# up-GEMM activation stores write-through (sc1)
# baseline (speedup 1.0000x reference)
.LBB0_659:
	s_mul_i32 s3, s19, 0xfc
	s_add_i32 s37, s61, s3
	s_add_i32 s8, s37, 0x1080
	s_ashr_i32 s9, s8, 31
	s_lshr_b32 s9, s9, 20
	s_add_i32 s8, s8, s9
	s_mul_i32 s9, s18, 0x1400
	s_add_i32 s83, s9, 0
	v_cvt_f32_i32_e32 v183, v109
	v_cvt_f32_i32_e32 v182, v108
	v_cvt_f32_i32_e32 v181, v105
	v_cvt_f32_i32_e32 v180, v104
	v_cvt_f32_i32_e32 v179, v101
	v_cvt_f32_i32_e32 v178, v100
	v_cvt_f32_i32_e32 v177, v97
	v_cvt_f32_i32_e32 v176, v96
	v_cvt_f32_i32_e32 v125, v125
	v_cvt_f32_i32_e32 v124, v124
	v_cvt_f32_i32_e32 v121, v121
	v_cvt_f32_i32_e32 v120, v120
	v_cvt_f32_i32_e32 v117, v117
	v_cvt_f32_i32_e32 v116, v116
	v_cvt_f32_i32_e32 v113, v113
	v_cvt_f32_i32_e32 v112, v112
	v_cvt_f32_i32_e32 v109, v77
	v_cvt_f32_i32_e32 v108, v76
	v_cvt_f32_i32_e32 v105, v73
	v_cvt_f32_i32_e32 v104, v72
	v_cvt_f32_i32_e32 v101, v69
	v_cvt_f32_i32_e32 v100, v68
	v_cvt_f32_i32_e32 v97, v65
	v_cvt_f32_i32_e32 v96, v64
	v_cvt_f32_i32_e32 v77, v93
	v_cvt_f32_i32_e32 v76, v92
	v_cvt_f32_i32_e32 v73, v89
	v_cvt_f32_i32_e32 v72, v88
	v_cvt_f32_i32_e32 v69, v85
	v_cvt_f32_i32_e32 v68, v84
	v_cvt_f32_i32_e32 v65, v81
	v_cvt_f32_i32_e32 v64, v80
	s_add_i32 s83, s83, 0x20340
	s_lshl_b32 s9, s60, 2
	s_add_i32 s3, s37, 0x1000
	s_and_b32 s8, s8, 0xfffff000
	s_add_i32 s33, s83, s9
	s_cmp_lt_i32 s8, s3
	s_cbranch_scc1 .LBB0_685
	v_mbcnt_lo_u32_b32 v80, -1, 0
	v_mbcnt_hi_u32_b32 v80, -1, v80
	s_lshl_b32 s3, s95, 7
	v_and_b32_e32 v81, 15, v80
	v_ashrrev_i32_e32 v84, 4, v80
	s_or_b32 s3, s3, s73
	v_lshl_add_u32 v80, v81, 5, s33
	v_add_u32_e32 v85, 0x1000, v80
	v_add_u32_e32 v80, 0x1010, v80
	ds_read2_b64 v[132:135], v85 offset1:1
	ds_read2_b64 v[128:131], v80 offset1:1
	v_lshl_add_u32 v80, v84, 2, s3
	s_lshl_b32 s3, s73, 2
	v_lshlrev_b32_e32 v185, 3, v81
	v_ashrrev_i32_e32 v81, 31, v80
	s_add_i32 s3, s83, s3
	v_lshlrev_b64 v[88:89], 2, v[80:81]
	s_mov_b64 s[8:9], 0x2c00
	v_lshl_add_u32 v202, v84, 4, s3
	v_lshl_add_u64 v[92:93], v[88:89], 0, s[8:9]
	v_add_u32_e32 v196, 0x800, v202
	v_lshl_add_u64 v[152:153], s[28:29], 0, v[92:93]
	ds_read2_b64 v[136:139], v196 offset1:1
	ds_read2_b64 v[144:147], v196 offset0:64 offset1:65
	ds_read2_b64 v[140:143], v196 offset0:128 offset1:129
	ds_read2_b64 v[148:151], v196 offset0:192 offset1:193
	global_load_dwordx2 v[152:153], v[152:153], off
	global_load_dword v227, v92, s[28:29] offset:8
	global_load_dword v220, v92, s[28:29] offset:12
	global_load_dword v237, v92, s[26:27] offset:8
	global_load_dword v241, v92, s[26:27] offset:12
	v_lshl_add_u64 v[92:93], s[26:27], 0, v[92:93]
	global_load_dwordx2 v[92:93], v[92:93], off
	v_lshl_add_u64 v[242:243], s[28:29], 0, v[88:89]
	v_lshl_add_u64 v[246:247], s[26:27], 0, v[88:89]
	global_load_dwordx4 v[242:245], v[242:243], off
	global_load_dwordx4 v[246:249], v[246:247], off
	s_mov_b32 s42, 0x3c010204
	v_add_u32_e32 v85, s37, v185
	v_and_b32_e32 v171, 0xfff, v85
	s_movk_i32 s3, 0xfff
	s_waitcnt lgkmcnt(0)
	v_pk_mul_f32 v[166:167], v[132:133], v[182:183] op_sel_hi:[0,1]
	v_pk_mul_f32 v[168:169], v[132:133], v[180:181] op_sel:[1,0]
	v_pk_fma_f32 v[174:175], v[144:145], v[166:167], v[148:149]
	v_pk_mul_f32 v[162:163], v[134:135], v[178:179] op_sel_hi:[0,1]
	v_mov_b32_e32 v184, v135
	v_pk_mul_f32 v[160:161], v[184:185], v[176:177] op_sel_hi:[0,1]
	v_pk_mul_f32 v[158:159], v[128:129], v[124:125] op_sel_hi:[0,1]
	s_mov_b32 s24, 0x3856241d
	v_pk_mul_f32 v[198:199], v[134:135], v[100:101] op_sel_hi:[0,1]
	v_pk_mul_f32 v[200:201], v[184:185], v[96:97] op_sel_hi:[0,1]
	v_pk_mul_f32 v[204:205], v[128:129], v[76:77] op_sel_hi:[0,1]
	v_pk_mul_f32 v[206:207], v[128:129], v[72:73] op_sel:[1,0]
	v_pk_mul_f32 v[208:209], v[130:131], v[68:69] op_sel_hi:[0,1]
	s_waitcnt vmcnt(0)
	v_max_f32_e32 v81, v152, v152
	v_max_f32_e32 v152, 0xda24260, v81
	v_max_f32_e32 v81, v153, v153
	v_max_f32_e32 v153, 0xda24260, v81
	v_pk_add_f32 v[92:93], v[92:93], 0 neg_lo:[1,1] neg_hi:[1,1]
	v_pk_mul_f32 v[152:153], v[152:153], s[42:43] op_sel_hi:[1,0]
	s_nop 0
	v_div_scale_f32 v81, s[8:9], v152, v152, v92
	v_rcp_f32_e32 v84, v81
	s_nop 0
	v_fma_f32 v154, -v81, v84, 1.0
	v_fmac_f32_e32 v84, v154, v84
	v_div_scale_f32 v154, vcc, v92, v152, v92
	v_mul_f32_e32 v155, v154, v84
	v_fma_f32 v156, -v81, v155, v154
	v_fmac_f32_e32 v155, v156, v84
	v_fma_f32 v81, -v81, v155, v154
	v_div_fmas_f32 v81, v81, v84, v155
	v_div_scale_f32 v84, s[8:9], v153, v153, v93
	v_div_fixup_f32 v81, v81, v152, v92
	v_rcp_f32_e32 v92, v84
	v_cmp_eq_u32_e64 s[8:9], s3, v171
	v_add_u32_e32 v171, 1, v85
	v_and_b32_e32 v171, 0xffe, v171
	v_fma_f32 v152, -v84, v92, 1.0
	v_fmac_f32_e32 v92, v152, v92
	v_div_scale_f32 v152, vcc, v93, v153, v93
	v_mul_f32_e32 v154, v152, v92
	v_fma_f32 v155, -v84, v154, v152
	v_fmac_f32_e32 v154, v155, v92
	v_fma_f32 v84, -v84, v154, v152
	v_cmp_eq_u32_e64 s[10:11], 0, v171
	v_sub_u32_e32 v171, 0xffd, v85
	v_div_fmas_f32 v84, v84, v92, v154
	v_and_b32_e32 v171, 0xffe, v171
	v_div_fixup_f32 v170, v84, v153, v93
	v_mov_b32_e32 v84, v131
	v_cmp_eq_u32_e64 s[12:13], 0, v171
	v_add_u32_e32 v171, 3, v85
	v_pk_mul_f32 v[92:93], v[84:85], v[112:113] op_sel_hi:[0,1]
	v_and_b32_e32 v171, 0xffe, v171
	v_mov_b32_e32 v164, v92
	v_mov_b32_e32 v165, v93
	v_cmp_eq_u32_e64 s[14:15], 0, v171
	v_sub_u32_e32 v171, 0xffb, v85
	v_mov_b32_dpp v164, v164 row_shr:1 row_mask:0xf bank_mask:0xf
	v_mov_b32_dpp v165, v165 row_shr:1 row_mask:0xf bank_mask:0xf
	v_and_b32_e32 v171, 0xffe, v171
	v_cndmask_b32_e64 v173, v169, v170, s[8:9]
	v_cndmask_b32_e64 v172, v168, v81, s[8:9]
	v_pk_fma_f32 v[164:165], v[136:137], v[164:165], v[174:175]
	v_cmp_eq_u32_e64 s[22:23], 0, v171
	v_add_u32_e32 v171, 5, v85
	v_mov_b32_e32 v154, v166
	v_mov_b32_e32 v155, v167
	v_pk_fma_f32 v[164:165], v[140:141], v[172:173], v[164:165]
	v_cndmask_b32_e64 v167, v167, v170, s[10:11]
	v_cndmask_b32_e64 v166, v166, v81, s[10:11]
	v_pk_fma_f32 v[172:173], v[144:145], v[168:169], v[148:149]
	v_pk_fma_f32 v[174:175], v[144:145], v[162:163], v[148:149]
	v_and_b32_e32 v171, 0xffe, v171
	v_pk_fma_f32 v[166:167], v[136:137], v[166:167], v[172:173]
	v_cndmask_b32_e64 v173, v161, v170, s[12:13]
	v_cndmask_b32_e64 v172, v160, v81, s[12:13]
	v_pk_fma_f32 v[168:169], v[136:137], v[168:169], v[174:175]
	v_cmp_eq_u32_e64 s[20:21], 0, v171
	v_sub_u32_e32 v171, 0xff9, v85
	v_pk_mul_f32 v[156:157], v[128:129], v[120:121] op_sel:[1,0]
	v_pk_fma_f32 v[166:167], v[140:141], v[162:163], v[166:167]
	v_pk_fma_f32 v[168:169], v[140:141], v[172:173], v[168:169]
	v_cndmask_b32_e64 v163, v163, v170, s[14:15]
	v_cndmask_b32_e64 v162, v162, v81, s[14:15]
	v_pk_fma_f32 v[172:173], v[144:145], v[160:161], v[148:149]
	v_pk_fma_f32 v[174:175], v[144:145], v[158:159], v[148:149]
	v_and_b32_e32 v171, 0xffe, v171
	v_pk_fma_f32 v[162:163], v[136:137], v[162:163], v[172:173]
	v_cndmask_b32_e64 v173, v157, v170, s[22:23]
	v_cndmask_b32_e64 v172, v156, v81, s[22:23]
	v_pk_fma_f32 v[160:161], v[136:137], v[160:161], v[174:175]
	v_cmp_eq_u32_e64 s[18:19], 0, v171
	v_add_u32_e32 v171, 7, v85
	v_pk_fma_f32 v[162:163], v[140:141], v[158:159], v[162:163]
	v_pk_fma_f32 v[160:161], v[140:141], v[172:173], v[160:161]
	v_cndmask_b32_e64 v159, v159, v170, s[20:21]
	v_cndmask_b32_e64 v158, v158, v81, s[20:21]
	v_pk_fma_f32 v[172:173], v[144:145], v[156:157], v[148:149]
	v_and_b32_e32 v171, 0xffe, v171
	v_pk_mul_f32 v[152:153], v[130:131], v[116:117] op_sel_hi:[0,1]
	v_pk_fma_f32 v[158:159], v[136:137], v[158:159], v[172:173]
	v_cmp_eq_u32_e64 s[16:17], 0, v171
	v_pk_fma_f32 v[158:159], v[140:141], v[152:153], v[158:159]
	v_cndmask_b32_e64 v173, v93, v170, s[18:19]
	v_cndmask_b32_e64 v172, v92, v81, s[18:19]
	v_pk_fma_f32 v[174:175], v[144:145], v[152:153], v[148:149]
	v_cndmask_b32_e64 v153, v153, v170, s[16:17]
	v_cndmask_b32_e64 v152, v152, v81, s[16:17]
	v_pk_fma_f32 v[92:93], v[144:145], v[92:93], v[148:149]
	v_mov_b32_dpp v154, v154 row_shl:1 row_mask:0xf bank_mask:0xf
	v_mov_b32_dpp v155, v155 row_shl:1 row_mask:0xf bank_mask:0xf
	v_pk_fma_f32 v[156:157], v[136:137], v[156:157], v[174:175]
	v_pk_fma_f32 v[92:93], v[136:137], v[152:153], v[92:93]
	v_pk_fma_f32 v[156:157], v[140:141], v[172:173], v[156:157]
	v_pk_fma_f32 v[92:93], v[140:141], v[154:155], v[92:93]
	v_and_b32_e32 v141, 0x7fffffff, v165
	v_and_b32_e32 v140, 0x7fffffff, v164
	v_mov_b64_e32 v[136:137], s[24:25]
	v_pk_fma_f32 v[144:145], v[140:141], s[80:81], v[136:137] op_sel_hi:[1,0,0]
	v_and_b32_e32 v149, 0x7fffffff, v167
	v_pk_fma_f32 v[144:145], v[140:141], v[144:145], s[84:85] op_sel_hi:[1,1,0]
	v_and_b32_e32 v148, 0x7fffffff, v166
	v_pk_fma_f32 v[144:145], v[140:141], v[144:145], s[86:87] op_sel_hi:[1,1,0]
	v_pk_fma_f32 v[186:187], v[148:149], s[80:81], v[136:137] op_sel_hi:[1,0,0]
	v_pk_fma_f32 v[144:145], v[140:141], v[144:145], s[82:83] op_sel_hi:[1,1,0]
	v_pk_fma_f32 v[186:187], v[148:149], v[186:187], s[84:85] op_sel_hi:[1,1,0]
	v_pk_fma_f32 v[144:145], v[140:141], v[144:145], s[94:95] op_sel_hi:[1,1,0]
	v_pk_fma_f32 v[186:187], v[148:149], v[186:187], s[86:87] op_sel_hi:[1,1,0]
	v_pk_fma_f32 v[144:145], v[140:141], v[144:145], s[92:93] op_sel_hi:[1,1,0]
	v_and_b32_e32 v175, 0x7fffffff, v169
	v_pk_mul_f32 v[144:145], v[144:145], v[144:145]
	v_and_b32_e32 v174, 0x7fffffff, v168
	v_pk_fma_f32 v[186:187], v[148:149], v[186:187], s[82:83] op_sel_hi:[1,1,0]
	v_pk_mul_f32 v[144:145], v[144:145], v[144:145]
	v_pk_fma_f32 v[188:189], v[174:175], s[80:81], v[136:137] op_sel_hi:[1,0,0]
	v_pk_fma_f32 v[186:187], v[148:149], v[186:187], s[94:95] op_sel_hi:[1,1,0]
	v_pk_mul_f32 v[144:145], v[144:145], v[144:145]
	v_pk_fma_f32 v[188:189], v[174:175], v[188:189], s[84:85] op_sel_hi:[1,1,0]
	v_pk_fma_f32 v[186:187], v[148:149], v[186:187], s[92:93] op_sel_hi:[1,1,0]
	v_pk_mul_f32 v[144:145], v[144:145], v[144:145]
	v_pk_fma_f32 v[188:189], v[174:175], v[188:189], s[86:87] op_sel_hi:[1,1,0]
	v_pk_mul_f32 v[186:187], v[186:187], v[186:187]
	v_rcp_f32_e32 v144, v144
	v_rcp_f32_e32 v145, v145
	v_and_b32_e32 v173, 0x7fffffff, v163
	v_and_b32_e32 v172, 0x7fffffff, v162
	v_pk_fma_f32 v[188:189], v[174:175], v[188:189], s[82:83] op_sel_hi:[1,1,0]
	v_pk_mul_f32 v[186:187], v[186:187], v[186:187]
	v_pk_fma_f32 v[190:191], v[172:173], s[80:81], v[136:137] op_sel_hi:[1,0,0]
	v_pk_fma_f32 v[188:189], v[174:175], v[188:189], s[94:95] op_sel_hi:[1,1,0]
	v_pk_mul_f32 v[186:187], v[186:187], v[186:187]
	v_pk_fma_f32 v[190:191], v[172:173], v[190:191], s[84:85] op_sel_hi:[1,1,0]
	v_pk_fma_f32 v[188:189], v[174:175], v[188:189], s[92:93] op_sel_hi:[1,1,0]
	v_pk_mul_f32 v[192:193], v[186:187], v[186:187]
	v_max_f32_e32 v165, 0, v165
	v_max_f32_e32 v164, 0, v164
	v_pk_fma_f32 v[190:191], v[172:173], v[190:191], s[86:87] op_sel_hi:[1,1,0]
	v_pk_mul_f32 v[188:189], v[188:189], v[188:189]
	v_pk_fma_f32 v[186:187], v[140:141], v[144:145], v[164:165] neg_lo:[1,0,0] neg_hi:[1,0,0]
	v_rcp_f32_e32 v140, v192
	v_rcp_f32_e32 v141, v193
	v_pk_fma_f32 v[190:191], v[172:173], v[190:191], s[82:83] op_sel_hi:[1,1,0]
	v_pk_mul_f32 v[188:189], v[188:189], v[188:189]
	v_pk_fma_f32 v[190:191], v[172:173], v[190:191], s[94:95] op_sel_hi:[1,1,0]
	v_pk_mul_f32 v[188:189], v[188:189], v[188:189]
	v_pk_fma_f32 v[190:191], v[172:173], v[190:191], s[92:93] op_sel_hi:[1,1,0]
	v_pk_mul_f32 v[188:189], v[188:189], v[188:189]
	v_max_f32_e32 v145, 0, v167
	v_max_f32_e32 v144, 0, v166
	v_pk_mul_f32 v[190:191], v[190:191], v[190:191]
	v_pk_fma_f32 v[148:149], v[148:149], v[140:141], v[144:145] neg_lo:[1,0,0] neg_hi:[1,0,0]
	v_rcp_f32_e32 v140, v188
	v_rcp_f32_e32 v141, v189
	v_pk_mul_f32 v[190:191], v[190:191], v[190:191]
	v_max_f32_e32 v145, 0, v169
	v_pk_mul_f32 v[190:191], v[190:191], v[190:191]
	v_max_f32_e32 v144, 0, v168
	v_pk_mul_f32 v[190:191], v[190:191], v[190:191]
	v_pk_fma_f32 v[144:145], v[174:175], v[140:141], v[144:145] neg_lo:[1,0,0] neg_hi:[1,0,0]
	v_rcp_f32_e32 v140, v190
	v_rcp_f32_e32 v141, v191
	v_max_f32_e32 v163, 0, v163
	v_max_f32_e32 v162, 0, v162
	v_and_b32_e32 v171, 0x7fffffff, v159
	v_pk_fma_f32 v[140:141], v[172:173], v[140:141], v[162:163] neg_lo:[1,0,0] neg_hi:[1,0,0]
	v_and_b32_e32 v163, 0x7fffffff, v161
	v_and_b32_e32 v162, 0x7fffffff, v160
	v_pk_fma_f32 v[164:165], v[162:163], s[80:81], v[136:137] op_sel_hi:[1,0,0]
	v_and_b32_e32 v170, 0x7fffffff, v158
	v_pk_fma_f32 v[164:165], v[162:163], v[164:165], s[84:85] op_sel_hi:[1,1,0]
	v_pk_fma_f32 v[166:167], v[170:171], s[80:81], v[136:137] op_sel_hi:[1,0,0]
	v_pk_fma_f32 v[164:165], v[162:163], v[164:165], s[86:87] op_sel_hi:[1,1,0]
	v_pk_fma_f32 v[166:167], v[170:171], v[166:167], s[84:85] op_sel_hi:[1,1,0]
	v_pk_fma_f32 v[164:165], v[162:163], v[164:165], s[82:83] op_sel_hi:[1,1,0]
	v_pk_fma_f32 v[166:167], v[170:171], v[166:167], s[86:87] op_sel_hi:[1,1,0]
	v_pk_fma_f32 v[164:165], v[162:163], v[164:165], s[94:95] op_sel_hi:[1,1,0]
	v_and_b32_e32 v155, 0x7fffffff, v157
	v_pk_fma_f32 v[164:165], v[162:163], v[164:165], s[92:93] op_sel_hi:[1,1,0]
	v_and_b32_e32 v154, 0x7fffffff, v156
	v_pk_mul_f32 v[164:165], v[164:165], v[164:165]
	v_pk_fma_f32 v[166:167], v[170:171], v[166:167], s[82:83] op_sel_hi:[1,1,0]
	v_pk_mul_f32 v[164:165], v[164:165], v[164:165]
	v_pk_fma_f32 v[168:169], v[154:155], s[80:81], v[136:137] op_sel_hi:[1,0,0]
	v_pk_fma_f32 v[166:167], v[170:171], v[166:167], s[94:95] op_sel_hi:[1,1,0]
	v_pk_mul_f32 v[164:165], v[164:165], v[164:165]
	v_pk_fma_f32 v[168:169], v[154:155], v[168:169], s[84:85] op_sel_hi:[1,1,0]
	v_pk_fma_f32 v[166:167], v[170:171], v[166:167], s[92:93] op_sel_hi:[1,1,0]
	v_pk_mul_f32 v[164:165], v[164:165], v[164:165]
	v_pk_fma_f32 v[168:169], v[154:155], v[168:169], s[86:87] op_sel_hi:[1,1,0]
	v_pk_mul_f32 v[166:167], v[166:167], v[166:167]
	v_rcp_f32_e32 v164, v164
	v_rcp_f32_e32 v165, v165
	v_and_b32_e32 v153, 0x7fffffff, v93
	v_and_b32_e32 v152, 0x7fffffff, v92
	v_pk_fma_f32 v[168:169], v[154:155], v[168:169], s[82:83] op_sel_hi:[1,1,0]
	v_pk_mul_f32 v[166:167], v[166:167], v[166:167]
	v_pk_fma_f32 v[172:173], v[152:153], s[80:81], v[136:137] op_sel_hi:[1,0,0]
	v_pk_fma_f32 v[168:169], v[154:155], v[168:169], s[94:95] op_sel_hi:[1,1,0]
	v_pk_mul_f32 v[166:167], v[166:167], v[166:167]
	v_pk_fma_f32 v[172:173], v[152:153], v[172:173], s[84:85] op_sel_hi:[1,1,0]
	v_pk_fma_f32 v[168:169], v[154:155], v[168:169], s[92:93] op_sel_hi:[1,1,0]
	v_pk_mul_f32 v[166:167], v[166:167], v[166:167]
	v_max_f32_e32 v161, 0, v161
	v_max_f32_e32 v160, 0, v160
	v_pk_fma_f32 v[172:173], v[152:153], v[172:173], s[86:87] op_sel_hi:[1,1,0]
	v_pk_mul_f32 v[168:169], v[168:169], v[168:169]
	v_pk_fma_f32 v[194:195], v[162:163], v[164:165], v[160:161] neg_lo:[1,0,0] neg_hi:[1,0,0]
	v_rcp_f32_e32 v160, v166
	v_rcp_f32_e32 v161, v167
	v_pk_fma_f32 v[172:173], v[152:153], v[172:173], s[82:83] op_sel_hi:[1,1,0]
	v_pk_mul_f32 v[168:169], v[168:169], v[168:169]
	v_pk_fma_f32 v[172:173], v[152:153], v[172:173], s[94:95] op_sel_hi:[1,1,0]
	v_pk_mul_f32 v[168:169], v[168:169], v[168:169]
	v_pk_fma_f32 v[172:173], v[152:153], v[172:173], s[92:93] op_sel_hi:[1,1,0]
	v_pk_mul_f32 v[168:169], v[168:169], v[168:169]
	v_max_f32_e32 v159, 0, v159
	v_max_f32_e32 v158, 0, v158
	v_pk_mul_f32 v[172:173], v[172:173], v[172:173]
	v_pk_fma_f32 v[192:193], v[170:171], v[160:161], v[158:159] neg_lo:[1,0,0] neg_hi:[1,0,0]
	v_rcp_f32_e32 v158, v168
	v_rcp_f32_e32 v159, v169
	v_pk_mul_f32 v[172:173], v[172:173], v[172:173]
	v_max_f32_e32 v157, 0, v157
	v_pk_mul_f32 v[172:173], v[172:173], v[172:173]
	v_max_f32_e32 v156, 0, v156
	v_pk_mul_f32 v[172:173], v[172:173], v[172:173]
	v_pk_fma_f32 v[190:191], v[154:155], v[158:159], v[156:157] neg_lo:[1,0,0] neg_hi:[1,0,0]
	v_rcp_f32_e32 v154, v172
	v_rcp_f32_e32 v155, v173
	v_max_f32_e32 v93, 0, v93
	v_max_f32_e32 v92, 0, v92
	v_pk_mul_f32 v[210:211], v[84:85], v[64:65] op_sel_hi:[0,1]
	v_pk_fma_f32 v[188:189], v[152:153], v[154:155], v[92:93] neg_lo:[1,0,0] neg_hi:[1,0,0]
	v_lshl_add_u64 v[92:93], s[28:29], 0, v[88:89]
	ds_read2_b64 v[156:159], v202 offset0:64 offset1:65
	ds_read2_b64 v[152:155], v202 offset0:128 offset1:129
	ds_read2_b64 v[160:163], v202 offset0:192 offset1:193
	v_mov_b64_e32 v[164:165], v[242:243]
	v_mov_b64_e32 v[166:167], v[244:245]
	v_lshl_add_u64 v[88:89], s[26:27], 0, v[88:89]
	v_mov_b64_e32 v[168:169], v[246:247]
	v_mov_b64_e32 v[170:171], v[248:249]
	v_mov_b32_e32 v212, v210
	v_mov_b32_e32 v213, v211
	s_movk_i32 s3, 0x2000
	v_mov_b32_dpp v212, v212 row_shr:1 row_mask:0xf bank_mask:0xf
	v_mov_b32_dpp v213, v213 row_shr:1 row_mask:0xf bank_mask:0xf
	s_waitcnt vmcnt(1)
	v_max_f32_e32 v81, v164, v164
	v_max_f32_e32 v164, 0xda24260, v81
	v_max_f32_e32 v81, v165, v165
	v_max_f32_e32 v165, 0xda24260, v81
	s_waitcnt vmcnt(0)
	v_pk_add_f32 v[168:169], v[168:169], 0 neg_lo:[1,1] neg_hi:[1,1]
	v_pk_mul_f32 v[164:165], v[164:165], s[42:43] op_sel_hi:[1,0]
	s_nop 0
	v_div_scale_f32 v81, s[24:25], v164, v164, v168
	v_rcp_f32_e32 v172, v81
	s_nop 0
	v_fma_f32 v173, -v81, v172, 1.0
	v_fmac_f32_e32 v172, v173, v172
	v_div_scale_f32 v173, vcc, v168, v164, v168
	v_mul_f32_e32 v174, v173, v172
	v_fma_f32 v175, -v81, v174, v173
	v_fmac_f32_e32 v174, v175, v172
	v_fma_f32 v81, -v81, v174, v173
	v_div_fmas_f32 v81, v81, v172, v174
	v_div_fixup_f32 v81, v81, v164, v168
	v_div_scale_f32 v164, s[24:25], v165, v165, v169
	v_rcp_f32_e32 v168, v164
	s_nop 0
	v_fma_f32 v172, -v164, v168, 1.0
	v_fmac_f32_e32 v168, v172, v168
	v_div_scale_f32 v172, vcc, v169, v165, v169
	v_mul_f32_e32 v173, v172, v168
	v_fma_f32 v174, -v164, v173, v172
	v_fmac_f32_e32 v173, v174, v168
	v_fma_f32 v164, -v164, v173, v172
	v_div_fmas_f32 v164, v164, v168, v173
	ds_read2_b64 v[172:175], v202 offset1:1
	v_div_fixup_f32 v203, v164, v165, v169
	v_pk_mul_f32 v[164:165], v[132:133], v[108:109] op_sel_hi:[0,1]
	v_pk_mul_f32 v[168:169], v[132:133], v[104:105] op_sel:[1,0]
	s_waitcnt lgkmcnt(1)
	v_pk_fma_f32 v[218:219], v[156:157], v[164:165], v[160:161]
	v_cndmask_b32_e64 v217, v169, v203, s[8:9]
	v_cndmask_b32_e64 v216, v168, v81, s[8:9]
	s_waitcnt lgkmcnt(0)
	v_pk_fma_f32 v[212:213], v[172:173], v[212:213], v[218:219]
	v_mov_b32_e32 v214, v164
	v_pk_fma_f32 v[212:213], v[152:153], v[216:217], v[212:213]
	v_mov_b32_e32 v215, v165
	v_pk_mul_f32 v[186:187], v[212:213], v[186:187]
	v_cndmask_b32_e64 v165, v165, v203, s[10:11]
	v_cvt_pk_fp8_f32 v197, v186, v187
	s_nop 0
	v_cndmask_b32_e64 v164, v164, v81, s[10:11]
	v_pk_fma_f32 v[186:187], v[156:157], v[168:169], v[160:161]
	v_mov_b32_dpp v214, v214 row_shl:1 row_mask:0xf bank_mask:0xf
	v_pk_fma_f32 v[164:165], v[172:173], v[164:165], v[186:187]
	v_mov_b32_dpp v215, v215 row_shl:1 row_mask:0xf bank_mask:0xf
	v_pk_fma_f32 v[164:165], v[152:153], v[198:199], v[164:165]
	s_nop 0
	v_pk_mul_f32 v[148:149], v[164:165], v[148:149]
	v_pk_fma_f32 v[164:165], v[156:157], v[198:199], v[160:161]
	v_cvt_pk_fp8_f32 v187, v148, v149
	s_nop 0
	v_cndmask_b32_e64 v149, v201, v203, s[12:13]
	v_cndmask_b32_e64 v148, v200, v81, s[12:13]
	v_pk_fma_f32 v[164:165], v[172:173], v[168:169], v[164:165]
	s_nop 0
	v_pk_fma_f32 v[148:149], v[152:153], v[148:149], v[164:165]
	s_nop 0
	v_pk_mul_f32 v[144:145], v[148:149], v[144:145]
	v_pk_fma_f32 v[148:149], v[156:157], v[200:201], v[160:161]
	v_cvt_pk_fp8_f32 v186, v144, v145
	s_nop 0
	v_cndmask_b32_e64 v145, v199, v203, s[14:15]
	v_cndmask_b32_e64 v144, v198, v81, s[14:15]
	v_pk_fma_f32 v[144:145], v[172:173], v[144:145], v[148:149]
	s_nop 0
	v_pk_fma_f32 v[144:145], v[152:153], v[204:205], v[144:145]
	s_nop 0
	v_pk_mul_f32 v[140:141], v[144:145], v[140:141]
	v_pk_fma_f32 v[144:145], v[156:157], v[204:205], v[160:161]
	v_cvt_pk_fp8_f32 v169, v140, v141
	s_nop 0
	v_cndmask_b32_e64 v141, v207, v203, s[22:23]
	v_cndmask_b32_e64 v140, v206, v81, s[22:23]
	v_pk_fma_f32 v[144:145], v[172:173], v[200:201], v[144:145]
	s_nop 0
	v_pk_fma_f32 v[140:141], v[152:153], v[140:141], v[144:145]
	v_pk_fma_f32 v[144:145], v[156:157], v[206:207], v[160:161]
	v_pk_mul_f32 v[140:141], v[140:141], v[194:195]
	s_nop 0
	v_cvt_pk_fp8_f32 v168, v140, v141
	s_nop 0
	v_cndmask_b32_e64 v141, v205, v203, s[20:21]
	v_cndmask_b32_e64 v140, v204, v81, s[20:21]
	v_pk_fma_f32 v[140:141], v[172:173], v[140:141], v[144:145]
	v_pk_fma_f32 v[144:145], v[156:157], v[208:209], v[160:161]
	v_pk_fma_f32 v[140:141], v[152:153], v[208:209], v[140:141]
	v_pk_fma_f32 v[144:145], v[172:173], v[206:207], v[144:145]
	v_pk_mul_f32 v[140:141], v[140:141], v[192:193]
	s_nop 0
	v_cvt_pk_fp8_f32 v165, v140, v141
	s_nop 0
	v_cndmask_b32_e64 v141, v211, v203, s[18:19]
	v_cndmask_b32_e64 v140, v210, v81, s[18:19]
	v_pk_fma_f32 v[140:141], v[152:153], v[140:141], v[144:145]
	v_pk_fma_f32 v[144:145], v[156:157], v[210:211], v[160:161]
	v_pk_mul_f32 v[140:141], v[140:141], v[190:191]
	v_cvt_f32_i32_e32 v157, v127
	v_cvt_pk_fp8_f32 v164, v140, v141
	s_nop 0
	v_cndmask_b32_e64 v141, v209, v203, s[16:17]
	v_cndmask_b32_e64 v140, v208, v81, s[16:17]
	v_pk_fma_f32 v[140:141], v[172:173], v[140:141], v[144:145]
	v_cvt_f32_i32_e32 v161, v123
	v_pk_fma_f32 v[140:141], v[152:153], v[214:215], v[140:141]
	v_cvt_f32_i32_e32 v160, v122
	v_pk_mul_f32 v[140:141], v[140:141], v[188:189]
	v_cvt_f32_i32_e32 v189, v115
	v_cvt_pk_fp8_f32 v81, v140, v141
	s_nop 0
	v_add_co_u32_e32 v140, vcc, s3, v92
	v_cvt_f32_i32_e32 v188, v114
	s_nop 0
	v_addc_co_u32_e32 v141, vcc, 0, v93, vcc
	v_mov_b32_e32 v140, v227
	v_mov_b32_e32 v141, v220
	v_add_co_u32_e32 v144, vcc, s3, v88
	v_pk_mul_f32 v[188:189], v[84:85], v[188:189] op_sel_hi:[0,1]
	s_nop 0
	v_addc_co_u32_e32 v145, vcc, 0, v89, vcc
	v_mov_b32_e32 v144, v237
	v_mov_b32_e32 v145, v241
	v_mov_b32_e32 v190, v188
	v_mov_b32_e32 v191, v189
	v_cvt_f32_i32_e32 v173, v119
	v_mov_b32_dpp v190, v190 row_shr:1 row_mask:0xf bank_mask:0xf
	v_mov_b32_dpp v191, v191 row_shr:1 row_mask:0xf bank_mask:0xf
	v_cvt_f32_i32_e32 v172, v118
	v_pk_mul_f32 v[160:161], v[128:129], v[160:161] op_sel:[1,0]
	s_waitcnt vmcnt(0)
	v_pk_mul_f32 v[172:173], v[130:131], v[172:173] op_sel_hi:[0,1]
	s_waitcnt vmcnt(1)
	v_max_f32_e32 v140, v140, v140
	v_max_f32_e32 v141, v141, v141
	v_max_f32_e32 v140, 0xda24260, v140
	v_max_f32_e32 v141, 0xda24260, v141
	v_pk_mul_f32 v[140:141], v[140:141], s[42:43] op_sel_hi:[1,0]
	s_waitcnt vmcnt(0)
	global_load_dwordx4 v[242:245], v[92:93], off offset:64
	global_load_dwordx4 v[246:249], v[88:89], off offset:64
	v_lshlrev_b32_e32 v227, 2, v80
	v_add_u32_e32 v227, 0x2c40, v227
	global_load_dword v220, v227, s[28:29]
	global_load_dword v237, v227, s[28:29] offset:4
	global_load_dword v241, v227, s[26:27]
	global_load_dword v227, v227, s[26:27] offset:4
	v_pk_add_f32 v[144:145], v[144:145], 0 neg_lo:[1,1] neg_hi:[1,1]
	s_nop 0
	v_div_scale_f32 v148, s[24:25], v140, v140, v144
	v_rcp_f32_e32 v149, v148
	s_nop 0
	v_fma_f32 v152, -v148, v149, 1.0
	v_fmac_f32_e32 v149, v152, v149
	v_div_scale_f32 v152, vcc, v144, v140, v144
	v_mul_f32_e32 v153, v152, v149
	v_fma_f32 v156, -v148, v153, v152
	v_fmac_f32_e32 v153, v156, v149
	v_fma_f32 v148, -v148, v153, v152
	v_div_fmas_f32 v148, v148, v149, v153
	v_div_fixup_f32 v200, v148, v140, v144
	v_div_scale_f32 v140, s[24:25], v141, v141, v145
	v_rcp_f32_e32 v144, v140
	v_cvt_f32_i32_e32 v153, v99
	v_cvt_f32_i32_e32 v156, v126
	v_fma_f32 v148, -v140, v144, 1.0
	v_fmac_f32_e32 v144, v148, v144
	v_div_scale_f32 v148, vcc, v145, v141, v145
	v_mul_f32_e32 v149, v148, v144
	v_fma_f32 v152, -v140, v149, v148
	v_fmac_f32_e32 v149, v152, v144
	v_fma_f32 v140, -v140, v149, v148
	v_div_fmas_f32 v140, v140, v144, v149
	v_div_fixup_f32 v201, v140, v141, v145
	v_cvt_f32_i32_e32 v141, v111
	v_cvt_f32_i32_e32 v140, v110
	v_cvt_f32_i32_e32 v145, v107
	v_cvt_f32_i32_e32 v144, v106
	v_cvt_f32_i32_e32 v149, v103
	v_cvt_f32_i32_e32 v148, v102
	v_cvt_f32_i32_e32 v152, v98
	v_pk_mul_f32 v[140:141], v[132:133], v[140:141] op_sel_hi:[0,1]
	v_pk_mul_f32 v[144:145], v[132:133], v[144:145] op_sel:[1,0]
	v_pk_fma_f32 v[198:199], v[146:147], v[140:141], v[150:151]
	v_pk_mul_f32 v[148:149], v[134:135], v[148:149] op_sel_hi:[0,1]
	v_cndmask_b32_e64 v195, v145, v201, s[8:9]
	v_cndmask_b32_e64 v194, v144, v200, s[8:9]
	v_pk_fma_f32 v[190:191], v[138:139], v[190:191], v[198:199]
	v_pk_mul_f32 v[152:153], v[184:185], v[152:153] op_sel_hi:[0,1]
	v_mov_b32_e32 v192, v140
	v_mov_b32_e32 v193, v141
	v_pk_fma_f32 v[190:191], v[142:143], v[194:195], v[190:191]
	v_cndmask_b32_e64 v141, v141, v201, s[10:11]
	v_cndmask_b32_e64 v140, v140, v200, s[10:11]
	v_pk_fma_f32 v[194:195], v[146:147], v[144:145], v[150:151]
	v_pk_fma_f32 v[198:199], v[146:147], v[148:149], v[150:151]
	v_pk_mul_f32 v[156:157], v[128:129], v[156:157] op_sel_hi:[0,1]
	v_pk_fma_f32 v[140:141], v[138:139], v[140:141], v[194:195]
	v_cndmask_b32_e64 v195, v153, v201, s[12:13]
	v_cndmask_b32_e64 v194, v152, v200, s[12:13]
	v_pk_fma_f32 v[144:145], v[138:139], v[144:145], v[198:199]
	v_pk_fma_f32 v[140:141], v[142:143], v[148:149], v[140:141]
	v_pk_fma_f32 v[144:145], v[142:143], v[194:195], v[144:145]
	v_cndmask_b32_e64 v149, v149, v201, s[14:15]
	v_cndmask_b32_e64 v148, v148, v200, s[14:15]
	v_pk_fma_f32 v[194:195], v[146:147], v[152:153], v[150:151]
	v_pk_fma_f32 v[198:199], v[146:147], v[156:157], v[150:151]
	v_pk_fma_f32 v[148:149], v[138:139], v[148:149], v[194:195]
	v_cndmask_b32_e64 v195, v161, v201, s[22:23]
	v_cndmask_b32_e64 v194, v160, v200, s[22:23]
	v_pk_fma_f32 v[152:153], v[138:139], v[152:153], v[198:199]
	v_pk_fma_f32 v[148:149], v[142:143], v[156:157], v[148:149]
	v_pk_fma_f32 v[152:153], v[142:143], v[194:195], v[152:153]
	v_cndmask_b32_e64 v157, v157, v201, s[20:21]
	v_cndmask_b32_e64 v156, v156, v200, s[20:21]
	v_pk_fma_f32 v[194:195], v[146:147], v[160:161], v[150:151]
	v_pk_fma_f32 v[198:199], v[146:147], v[172:173], v[150:151]
	v_pk_fma_f32 v[156:157], v[138:139], v[156:157], v[194:195]
	v_pk_fma_f32 v[146:147], v[146:147], v[188:189], v[150:151]
	v_pk_fma_f32 v[156:157], v[142:143], v[172:173], v[156:157]
	v_cndmask_b32_e64 v173, v173, v201, s[16:17]
	v_cndmask_b32_e64 v172, v172, v200, s[16:17]
	v_mov_b32_dpp v192, v192 row_shl:1 row_mask:0xf bank_mask:0xf
	v_mov_b32_dpp v193, v193 row_shl:1 row_mask:0xf bank_mask:0xf
	v_pk_fma_f32 v[160:161], v[138:139], v[160:161], v[198:199]
	v_pk_fma_f32 v[138:139], v[138:139], v[172:173], v[146:147]
	v_cndmask_b32_e64 v195, v189, v201, s[18:19]
	v_cndmask_b32_e64 v194, v188, v200, s[18:19]
	v_pk_fma_f32 v[146:147], v[142:143], v[192:193], v[138:139]
	v_and_b32_e32 v139, 0x7fffffff, v191
	v_and_b32_e32 v138, 0x7fffffff, v190
	v_pk_fma_f32 v[160:161], v[142:143], v[194:195], v[160:161]
	v_pk_fma_f32 v[142:143], v[138:139], s[80:81], v[136:137] op_sel_hi:[1,0,0]
	v_and_b32_e32 v199, 0x7fffffff, v141
	v_pk_fma_f32 v[142:143], v[138:139], v[142:143], s[84:85] op_sel_hi:[1,1,0]
	v_and_b32_e32 v198, 0x7fffffff, v140
	v_pk_fma_f32 v[142:143], v[138:139], v[142:143], s[86:87] op_sel_hi:[1,1,0]
	v_pk_fma_f32 v[200:201], v[198:199], s[80:81], v[136:137] op_sel_hi:[1,0,0]
	v_pk_fma_f32 v[142:143], v[138:139], v[142:143], s[82:83] op_sel_hi:[1,1,0]
	v_pk_fma_f32 v[200:201], v[198:199], v[200:201], s[84:85] op_sel_hi:[1,1,0]
	v_pk_fma_f32 v[142:143], v[138:139], v[142:143], s[94:95] op_sel_hi:[1,1,0]
	v_pk_fma_f32 v[200:201], v[198:199], v[200:201], s[86:87] op_sel_hi:[1,1,0]
	v_pk_fma_f32 v[142:143], v[138:139], v[142:143], s[92:93] op_sel_hi:[1,1,0]
	v_and_b32_e32 v195, 0x7fffffff, v145
	v_pk_mul_f32 v[142:143], v[142:143], v[142:143]
	v_and_b32_e32 v194, 0x7fffffff, v144
	v_pk_fma_f32 v[200:201], v[198:199], v[200:201], s[82:83] op_sel_hi:[1,1,0]
	v_pk_mul_f32 v[142:143], v[142:143], v[142:143]
	v_pk_fma_f32 v[204:205], v[194:195], s[80:81], v[136:137] op_sel_hi:[1,0,0]
	v_pk_fma_f32 v[200:201], v[198:199], v[200:201], s[94:95] op_sel_hi:[1,1,0]
	v_pk_mul_f32 v[142:143], v[142:143], v[142:143]
	v_pk_fma_f32 v[204:205], v[194:195], v[204:205], s[84:85] op_sel_hi:[1,1,0]
	v_pk_fma_f32 v[200:201], v[198:199], v[200:201], s[92:93] op_sel_hi:[1,1,0]
	v_pk_mul_f32 v[142:143], v[142:143], v[142:143]
	v_pk_fma_f32 v[204:205], v[194:195], v[204:205], s[86:87] op_sel_hi:[1,1,0]
	v_pk_mul_f32 v[200:201], v[200:201], v[200:201]
	v_rcp_f32_e32 v142, v142
	v_rcp_f32_e32 v143, v143
	v_and_b32_e32 v193, 0x7fffffff, v149
	v_and_b32_e32 v192, 0x7fffffff, v148
	v_pk_fma_f32 v[204:205], v[194:195], v[204:205], s[82:83] op_sel_hi:[1,1,0]
	v_pk_mul_f32 v[200:201], v[200:201], v[200:201]
	v_pk_fma_f32 v[206:207], v[192:193], s[80:81], v[136:137] op_sel_hi:[1,0,0]
	v_pk_fma_f32 v[204:205], v[194:195], v[204:205], s[94:95] op_sel_hi:[1,1,0]
	v_pk_mul_f32 v[200:201], v[200:201], v[200:201]
	v_pk_fma_f32 v[206:207], v[192:193], v[206:207], s[84:85] op_sel_hi:[1,1,0]
	v_pk_fma_f32 v[204:205], v[194:195], v[204:205], s[92:93] op_sel_hi:[1,1,0]
	v_pk_mul_f32 v[200:201], v[200:201], v[200:201]
	v_max_f32_e32 v191, 0, v191
	v_max_f32_e32 v190, 0, v190
	v_pk_fma_f32 v[206:207], v[192:193], v[206:207], s[86:87] op_sel_hi:[1,1,0]
	v_pk_mul_f32 v[204:205], v[204:205], v[204:205]
	v_pk_fma_f32 v[138:139], v[138:139], v[142:143], v[190:191] neg_lo:[1,0,0] neg_hi:[1,0,0]
	v_rcp_f32_e32 v142, v200
	v_rcp_f32_e32 v143, v201
	v_pk_fma_f32 v[206:207], v[192:193], v[206:207], s[82:83] op_sel_hi:[1,1,0]
	v_pk_mul_f32 v[204:205], v[204:205], v[204:205]
	v_pk_fma_f32 v[206:207], v[192:193], v[206:207], s[94:95] op_sel_hi:[1,1,0]
	v_pk_mul_f32 v[204:205], v[204:205], v[204:205]
	v_pk_fma_f32 v[206:207], v[192:193], v[206:207], s[92:93] op_sel_hi:[1,1,0]
	v_pk_mul_f32 v[204:205], v[204:205], v[204:205]
	v_max_f32_e32 v141, 0, v141
	v_max_f32_e32 v140, 0, v140
	v_pk_mul_f32 v[206:207], v[206:207], v[206:207]
	v_pk_fma_f32 v[142:143], v[198:199], v[142:143], v[140:141] neg_lo:[1,0,0] neg_hi:[1,0,0]
	v_rcp_f32_e32 v140, v204
	v_rcp_f32_e32 v141, v205
	v_pk_mul_f32 v[206:207], v[206:207], v[206:207]
	v_max_f32_e32 v145, 0, v145
	v_pk_mul_f32 v[206:207], v[206:207], v[206:207]
	v_max_f32_e32 v144, 0, v144
	v_pk_mul_f32 v[206:207], v[206:207], v[206:207]
	v_pk_fma_f32 v[140:141], v[194:195], v[140:141], v[144:145] neg_lo:[1,0,0] neg_hi:[1,0,0]
	v_rcp_f32_e32 v144, v206
	v_rcp_f32_e32 v145, v207
	v_max_f32_e32 v149, 0, v149
	v_max_f32_e32 v148, 0, v148
	v_and_b32_e32 v173, 0x7fffffff, v147
	v_pk_fma_f32 v[144:145], v[192:193], v[144:145], v[148:149] neg_lo:[1,0,0] neg_hi:[1,0,0]
	v_and_b32_e32 v149, 0x7fffffff, v153
	v_and_b32_e32 v148, 0x7fffffff, v152
	v_and_b32_e32 v172, 0x7fffffff, v146
	v_and_b32_e32 v151, 0x7fffffff, v161
	v_and_b32_e32 v150, 0x7fffffff, v160
	v_and_b32_e32 v189, 0x7fffffff, v157
	v_and_b32_e32 v188, 0x7fffffff, v156
	v_pk_fma_f32 v[190:191], v[148:149], s[80:81], v[136:137] op_sel_hi:[1,0,0]
	v_pk_fma_f32 v[192:193], v[188:189], s[80:81], v[136:137] op_sel_hi:[1,0,0]
	v_pk_fma_f32 v[194:195], v[150:151], s[80:81], v[136:137] op_sel_hi:[1,0,0]
	v_pk_fma_f32 v[136:137], v[172:173], s[80:81], v[136:137] op_sel_hi:[1,0,0]
	v_pk_fma_f32 v[190:191], v[148:149], v[190:191], s[84:85] op_sel_hi:[1,1,0]
	v_pk_fma_f32 v[136:137], v[172:173], v[136:137], s[84:85] op_sel_hi:[1,1,0]
	v_pk_fma_f32 v[190:191], v[148:149], v[190:191], s[86:87] op_sel_hi:[1,1,0]
	v_pk_fma_f32 v[136:137], v[172:173], v[136:137], s[86:87] op_sel_hi:[1,1,0]
	v_pk_fma_f32 v[190:191], v[148:149], v[190:191], s[82:83] op_sel_hi:[1,1,0]
	v_pk_fma_f32 v[136:137], v[172:173], v[136:137], s[82:83] op_sel_hi:[1,1,0]
	v_pk_fma_f32 v[190:191], v[148:149], v[190:191], s[94:95] op_sel_hi:[1,1,0]
	v_pk_fma_f32 v[192:193], v[188:189], v[192:193], s[84:85] op_sel_hi:[1,1,0]
	v_pk_fma_f32 v[136:137], v[172:173], v[136:137], s[94:95] op_sel_hi:[1,1,0]
	v_pk_fma_f32 v[190:191], v[148:149], v[190:191], s[92:93] op_sel_hi:[1,1,0]
	v_pk_fma_f32 v[192:193], v[188:189], v[192:193], s[86:87] op_sel_hi:[1,1,0]
	v_pk_fma_f32 v[136:137], v[172:173], v[136:137], s[92:93] op_sel_hi:[1,1,0]
	v_pk_mul_f32 v[190:191], v[190:191], v[190:191]
	v_pk_fma_f32 v[192:193], v[188:189], v[192:193], s[82:83] op_sel_hi:[1,1,0]
	v_pk_mul_f32 v[136:137], v[136:137], v[136:137]
	v_pk_mul_f32 v[190:191], v[190:191], v[190:191]
	v_pk_fma_f32 v[192:193], v[188:189], v[192:193], s[94:95] op_sel_hi:[1,1,0]
	v_pk_mul_f32 v[136:137], v[136:137], v[136:137]
	v_pk_mul_f32 v[190:191], v[190:191], v[190:191]
	v_pk_fma_f32 v[194:195], v[150:151], v[194:195], s[84:85] op_sel_hi:[1,1,0]
	v_pk_fma_f32 v[192:193], v[188:189], v[192:193], s[92:93] op_sel_hi:[1,1,0]
	v_pk_mul_f32 v[136:137], v[136:137], v[136:137]
	v_pk_mul_f32 v[190:191], v[190:191], v[190:191]
	v_pk_fma_f32 v[194:195], v[150:151], v[194:195], s[86:87] op_sel_hi:[1,1,0]
	v_pk_mul_f32 v[192:193], v[192:193], v[192:193]
	v_pk_mul_f32 v[198:199], v[136:137], v[136:137]
	v_rcp_f32_e32 v136, v190
	v_rcp_f32_e32 v137, v191
	v_pk_fma_f32 v[194:195], v[150:151], v[194:195], s[82:83] op_sel_hi:[1,1,0]
	v_pk_mul_f32 v[192:193], v[192:193], v[192:193]
	v_pk_fma_f32 v[194:195], v[150:151], v[194:195], s[94:95] op_sel_hi:[1,1,0]
	v_pk_mul_f32 v[192:193], v[192:193], v[192:193]
	v_pk_fma_f32 v[194:195], v[150:151], v[194:195], s[92:93] op_sel_hi:[1,1,0]
	v_pk_mul_f32 v[192:193], v[192:193], v[192:193]
	v_max_f32_e32 v153, 0, v153
	v_max_f32_e32 v152, 0, v152
	v_pk_mul_f32 v[194:195], v[194:195], v[194:195]
	v_pk_fma_f32 v[148:149], v[148:149], v[136:137], v[152:153] neg_lo:[1,0,0] neg_hi:[1,0,0]
	v_rcp_f32_e32 v136, v192
	v_rcp_f32_e32 v137, v193
	v_pk_mul_f32 v[194:195], v[194:195], v[194:195]
	v_max_f32_e32 v153, 0, v157
	v_pk_mul_f32 v[194:195], v[194:195], v[194:195]
	v_max_f32_e32 v152, 0, v156
	v_pk_mul_f32 v[194:195], v[194:195], v[194:195]
	v_pk_fma_f32 v[136:137], v[188:189], v[136:137], v[152:153] neg_lo:[1,0,0] neg_hi:[1,0,0]
	v_rcp_f32_e32 v152, v194
	v_rcp_f32_e32 v153, v195
	v_max_f32_e32 v157, 0, v161
	v_max_f32_e32 v156, 0, v160
	v_max_f32_e32 v147, 0, v147
	v_pk_fma_f32 v[150:151], v[150:151], v[152:153], v[156:157] neg_lo:[1,0,0] neg_hi:[1,0,0]
	v_rcp_f32_e32 v152, v198
	v_rcp_f32_e32 v153, v199
	v_max_f32_e32 v146, 0, v146
	v_pk_add_f32 v[156:157], v[170:171], 0 neg_lo:[1,1] neg_hi:[1,1]
	v_cvt_f32_i32_e32 v191, v83
	v_pk_fma_f32 v[146:147], v[172:173], v[152:153], v[146:147] neg_lo:[1,0,0] neg_hi:[1,0,0]
	v_max_f32_e32 v152, v166, v166
	v_max_f32_e32 v153, v167, v167
	v_max_f32_e32 v152, 0xda24260, v152
	v_max_f32_e32 v153, 0xda24260, v153
	v_pk_mul_f32 v[152:153], v[152:153], s[42:43] op_sel_hi:[1,0]
	v_cvt_f32_i32_e32 v190, v82
	v_div_scale_f32 v160, s[24:25], v152, v152, v156
	v_rcp_f32_e32 v161, v160
	v_pk_mul_f32 v[190:191], v[84:85], v[190:191] op_sel_hi:[0,1]
	v_mov_b32_e32 v192, v190
	v_mov_b32_e32 v193, v191
	v_fma_f32 v166, -v160, v161, 1.0
	v_fmac_f32_e32 v161, v166, v161
	v_div_scale_f32 v166, vcc, v156, v152, v156
	v_mul_f32_e32 v167, v166, v161
	v_fma_f32 v170, -v160, v167, v166
	v_fmac_f32_e32 v167, v170, v161
	v_fma_f32 v160, -v160, v167, v166
	v_div_fmas_f32 v160, v160, v161, v167
	v_div_fixup_f32 v203, v160, v152, v156
	v_div_scale_f32 v152, s[24:25], v153, v153, v157
	v_rcp_f32_e32 v156, v152
	v_mov_b32_dpp v192, v192 row_shr:1 row_mask:0xf bank_mask:0xf
	v_mov_b32_dpp v193, v193 row_shr:1 row_mask:0xf bank_mask:0xf
	v_cvt_f32_i32_e32 v167, v67
	v_fma_f32 v160, -v152, v156, 1.0
	v_fmac_f32_e32 v156, v160, v156
	v_div_scale_f32 v160, vcc, v157, v153, v157
	v_mul_f32_e32 v161, v160, v156
	v_fma_f32 v166, -v152, v161, v160
	v_fmac_f32_e32 v161, v166, v156
	v_fma_f32 v152, -v152, v161, v160
	v_div_fmas_f32 v152, v152, v156, v161
	v_div_fixup_f32 v204, v152, v153, v157
	v_cvt_f32_i32_e32 v153, v79
	v_cvt_f32_i32_e32 v152, v78
	v_cvt_f32_i32_e32 v157, v75
	v_cvt_f32_i32_e32 v156, v74
	v_cvt_f32_i32_e32 v161, v71
	v_pk_mul_f32 v[152:153], v[132:133], v[152:153] op_sel_hi:[0,1]
	v_pk_fma_f32 v[200:201], v[158:159], v[152:153], v[162:163]
	v_pk_mul_f32 v[156:157], v[132:133], v[156:157] op_sel:[1,0]
	v_cvt_f32_i32_e32 v160, v70
	v_cndmask_b32_e64 v199, v157, v204, s[8:9]
	v_cndmask_b32_e64 v198, v156, v203, s[8:9]
	v_pk_fma_f32 v[192:193], v[174:175], v[192:193], v[200:201]
	v_cvt_f32_i32_e32 v166, v66
	v_pk_fma_f32 v[192:193], v[154:155], v[198:199], v[192:193]
	v_mov_b32_e32 v194, v152
	v_pk_mul_f32 v[138:139], v[192:193], v[138:139]
	v_mov_b32_e32 v195, v153
	v_cvt_pk_fp8_f32 v197, v138, v139 op_sel:[0,0,1]
	s_nop 0
	v_cndmask_b32_e64 v139, v153, v204, s[10:11]
	v_cndmask_b32_e64 v138, v152, v203, s[10:11]
	v_pk_fma_f32 v[152:153], v[158:159], v[156:157], v[162:163]
	v_pk_mul_f32 v[160:161], v[134:135], v[160:161] op_sel_hi:[0,1]
	v_pk_fma_f32 v[138:139], v[174:175], v[138:139], v[152:153]
	v_pk_mul_f32 v[166:167], v[184:185], v[166:167] op_sel_hi:[0,1]
	v_pk_fma_f32 v[138:139], v[154:155], v[160:161], v[138:139]
	v_cvt_f32_i32_e32 v171, v95
	v_pk_mul_f32 v[138:139], v[138:139], v[142:143]
	v_pk_fma_f32 v[142:143], v[158:159], v[160:161], v[162:163]
	v_cvt_f32_i32_e32 v170, v94
	v_cvt_pk_fp8_f32 v187, v138, v139 op_sel:[0,0,1]
	s_nop 0
	v_cndmask_b32_e64 v139, v167, v204, s[12:13]
	v_cndmask_b32_e64 v138, v166, v203, s[12:13]
	v_pk_fma_f32 v[142:143], v[174:175], v[156:157], v[142:143]
	v_cvt_f32_i32_e32 v173, v91
	v_pk_fma_f32 v[138:139], v[154:155], v[138:139], v[142:143]
	v_cvt_f32_i32_e32 v172, v90
	v_pk_mul_f32 v[138:139], v[138:139], v[140:141]
	v_pk_fma_f32 v[140:141], v[158:159], v[166:167], v[162:163]
	v_cvt_pk_fp8_f32 v186, v138, v139 op_sel:[0,0,1]
	s_nop 0
	v_cndmask_b32_e64 v139, v161, v204, s[14:15]
	v_cndmask_b32_e64 v138, v160, v203, s[14:15]
	v_pk_mul_f32 v[170:171], v[128:129], v[170:171] op_sel_hi:[0,1]
	v_pk_fma_f32 v[138:139], v[174:175], v[138:139], v[140:141]
	v_pk_mul_f32 v[172:173], v[128:129], v[172:173] op_sel:[1,0]
	v_pk_fma_f32 v[138:139], v[154:155], v[170:171], v[138:139]
	v_pk_fma_f32 v[140:141], v[158:159], v[170:171], v[162:163]
	v_pk_mul_f32 v[138:139], v[138:139], v[144:145]
	v_cvt_f32_i32_e32 v189, v87
	v_cvt_f32_i32_e32 v188, v86
	v_cvt_pk_fp8_f32 v169, v138, v139 op_sel:[0,0,1]
	s_nop 0
	v_cndmask_b32_e64 v139, v173, v204, s[22:23]
	v_cndmask_b32_e64 v138, v172, v203, s[22:23]
	v_pk_fma_f32 v[140:141], v[174:175], v[166:167], v[140:141]
	v_pk_mul_f32 v[188:189], v[130:131], v[188:189] op_sel_hi:[0,1]
	v_pk_fma_f32 v[138:139], v[154:155], v[138:139], v[140:141]
	v_pk_fma_f32 v[140:141], v[158:159], v[172:173], v[162:163]
	v_pk_mul_f32 v[138:139], v[138:139], v[148:149]
	v_add_u32_e32 v84, -1, v185
	v_cvt_pk_fp8_f32 v168, v138, v139 op_sel:[0,0,1]
	s_nop 0
	v_cndmask_b32_e64 v139, v171, v204, s[20:21]
	v_cndmask_b32_e64 v138, v170, v203, s[20:21]
	v_pk_fma_f32 v[138:139], v[174:175], v[138:139], v[140:141]
	v_mov_b32_dpp v194, v194 row_shl:1 row_mask:0xf bank_mask:0xf
	v_pk_fma_f32 v[138:139], v[154:155], v[188:189], v[138:139]
	v_mov_b32_dpp v195, v195 row_shl:1 row_mask:0xf bank_mask:0xf
	v_pk_mul_f32 v[136:137], v[138:139], v[136:137]
	v_pk_fma_f32 v[138:139], v[158:159], v[188:189], v[162:163]
	v_cvt_pk_fp8_f32 v165, v136, v137 op_sel:[0,0,1]
	s_nop 0
	v_cndmask_b32_e64 v137, v191, v204, s[18:19]
	v_cndmask_b32_e64 v136, v190, v203, s[18:19]
	v_pk_fma_f32 v[138:139], v[174:175], v[172:173], v[138:139]
	v_cmp_gt_u32_e32 vcc, s87, v84
	v_pk_fma_f32 v[136:137], v[154:155], v[136:137], v[138:139]
	v_pk_fma_f32 v[138:139], v[158:159], v[190:191], v[162:163]
	v_pk_mul_f32 v[136:137], v[136:137], v[150:151]
	v_cmp_gt_i32_e64 s[24:25], s81, v85
	v_cvt_pk_fp8_f32 v164, v136, v137 op_sel:[0,0,1]
	s_nop 0
	v_cndmask_b32_e64 v137, v189, v204, s[16:17]
	v_cndmask_b32_e64 v136, v188, v203, s[16:17]
	v_pk_fma_f32 v[136:137], v[174:175], v[136:137], v[138:139]
	s_and_b64 s[42:43], vcc, s[24:25]
	v_pk_fma_f32 v[136:137], v[154:155], v[194:195], v[136:137]
	s_nop 0
	v_pk_mul_f32 v[136:137], v[136:137], v[146:147]
	s_nop 0
	v_cvt_pk_fp8_f32 v81, v136, v137 op_sel:[0,0,1]
	s_nop 0
	s_waitcnt vmcnt(0)
	s_and_saveexec_b64 s[24:25], s[42:43]
	s_cbranch_execz .LBB0_662
	s_movk_i32 s3, 0xb00
	v_mad_u64_u32 v[136:137], s[44:45], v85, s3, v[80:81]
	buffer_store_dword v197, v136, s[88:91], 0 offen sc1
.LBB0_662:
	s_or_b64 exec, exec, s[24:25]
	v_or_b32_e32 v84, 1, v185
	v_add_u32_e32 v204, s37, v84
	v_cmp_gt_u32_e32 vcc, s87, v185
	v_cmp_gt_i32_e64 s[24:25], s81, v204
	s_and_b64 s[44:45], vcc, s[24:25]
	s_and_saveexec_b64 s[24:25], s[44:45]
	s_cbranch_execz .LBB0_664
	s_movk_i32 s3, 0xb00
	v_mad_u64_u32 v[136:137], s[46:47], v204, s3, v[80:81]
	buffer_store_dword v187, v136, s[88:91], 0 offen sc1
.LBB0_664:
	s_or_b64 exec, exec, s[24:25]
	v_or_b32_e32 v84, 2, v185
	v_add_u32_e32 v205, s37, v84
	v_cmp_gt_i32_e64 s[24:25], s81, v205
	s_and_b64 s[46:47], vcc, s[24:25]
	s_and_saveexec_b64 s[24:25], s[46:47]
	s_cbranch_execz .LBB0_666
	s_movk_i32 s3, 0xb00
	v_mad_u64_u32 v[136:137], s[48:49], v205, s3, v[80:81]
	buffer_store_dword v186, v136, s[88:91], 0 offen sc1
.LBB0_666:
	s_or_b64 exec, exec, s[24:25]
	v_or_b32_e32 v136, 3, v185
	v_add_u32_e32 v206, s37, v136
	v_cmp_gt_u32_e32 vcc, s87, v84
	v_cmp_gt_i32_e64 s[24:25], s81, v206
	s_and_b64 s[48:49], vcc, s[24:25]
	s_and_saveexec_b64 s[24:25], s[48:49]
	s_cbranch_execz .LBB0_668
	s_movk_i32 s3, 0xb00
	v_mad_u64_u32 v[136:137], s[50:51], v206, s3, v[80:81]
	buffer_store_dword v169, v136, s[88:91], 0 offen sc1
.LBB0_668:
	s_or_b64 exec, exec, s[24:25]
	v_or_b32_e32 v84, 4, v185
	v_add_u32_e32 v207, s37, v84
	v_cmp_gt_i32_e64 s[24:25], s81, v207
	s_and_b64 s[50:51], vcc, s[24:25]
	s_and_saveexec_b64 s[24:25], s[50:51]
	s_cbranch_execz .LBB0_670
	s_movk_i32 s3, 0xb00
	v_mad_u64_u32 v[136:137], s[52:53], v207, s3, v[80:81]
	buffer_store_dword v168, v136, s[88:91], 0 offen sc1
.LBB0_670:
	s_or_b64 exec, exec, s[24:25]
	v_or_b32_e32 v136, 5, v185
	v_add_u32_e32 v208, s37, v136
	v_cmp_gt_u32_e32 vcc, s87, v84
	v_cmp_gt_i32_e64 s[24:25], s81, v208
	s_and_b64 s[52:53], vcc, s[24:25]
	s_and_saveexec_b64 s[24:25], s[52:53]
	s_cbranch_execz .LBB0_672
	s_movk_i32 s3, 0xb00
	v_mad_u64_u32 v[136:137], s[54:55], v208, s3, v[80:81]
	buffer_store_dword v165, v136, s[88:91], 0 offen sc1
.LBB0_672:
	s_or_b64 exec, exec, s[24:25]
	v_or_b32_e32 v84, 6, v185
	v_add_u32_e32 v209, s37, v84
	v_cmp_gt_i32_e64 s[24:25], s81, v209
	s_and_b64 s[54:55], vcc, s[24:25]
	s_and_saveexec_b64 s[24:25], s[54:55]
	s_cbranch_execz .LBB0_674
	s_movk_i32 s3, 0xb00
	v_mad_u64_u32 v[136:137], s[56:57], v209, s3, v[80:81]
	buffer_store_dword v164, v136, s[88:91], 0 offen sc1
.LBB0_674:
	s_or_b64 exec, exec, s[24:25]
	v_or_b32_e32 v84, 7, v185
	v_add_u32_e32 v203, s37, v84
	s_movk_i32 s3, 0x7f
	v_cmp_gt_u32_e32 vcc, s3, v84
	v_cmp_gt_i32_e64 s[24:25], s81, v203
	s_and_b64 s[24:25], vcc, s[24:25]
	s_and_saveexec_b64 s[56:57], s[24:25]
	s_cbranch_execz .LBB0_676
	s_movk_i32 s3, 0xb00
	v_mad_u64_u32 v[136:137], vcc, v203, s3, v[80:81]
	buffer_store_dword v81, v136, s[88:91], 0 offen sc1

.LBB0_683:
	s_movk_i32 s3, 0xb00
	v_mad_u64_u32 v[80:81], s[10:11], v209, s3, v[84:85]
	buffer_store_dword v149, v80, s[88:91], 0 offen sc1

.LBB0_685:
	s_mov_b64 s[24:25], 0
	s_cbranch_execz .LBB0_711
	v_mbcnt_lo_u32_b32 v80, -1, 0
	v_mbcnt_hi_u32_b32 v80, -1, v80
	s_lshl_b32 s3, s95, 7
	v_and_b32_e32 v81, 15, v80
	v_ashrrev_i32_e32 v80, 4, v80
	s_or_b32 s3, s3, s73
	v_lshl_add_u32 v84, v81, 5, s33
	v_add_u32_e32 v85, 0x1000, v84
	v_lshl_add_u32 v164, v80, 2, s3
	s_lshl_b32 s3, s73, 2
	v_add_u32_e32 v84, 0x1010, v84
	ds_read2_b64 v[132:135], v85 offset1:1
	ds_read2_b64 v[128:131], v84 offset1:1
	s_add_i32 s83, s83, s3
	v_lshl_add_u32 v92, v80, 4, s83
	v_add_u32_e32 v85, 0x800, v92
	ds_read2_b64 v[146:149], v85 offset1:1
	ds_read2_b64 v[156:159], v85 offset0:64 offset1:65
	ds_read2_b64 v[152:155], v85 offset0:128 offset1:129
	ds_read2_b64 v[160:163], v85 offset0:192 offset1:193
	v_lshlrev_b32_e32 v81, 3, v81
	s_waitcnt lgkmcnt(0)
	v_mov_b32_e32 v80, v131
	v_pk_mul_f32 v[112:113], v[80:81], v[112:113] op_sel_hi:[0,1]
	v_pk_mul_f32 v[88:89], v[132:133], v[182:183] op_sel_hi:[0,1]
	v_mov_b32_e32 v142, v112
	v_mov_b32_e32 v143, v113
	v_pk_mul_f32 v[136:137], v[132:133], v[180:181] op_sel:[1,0]
	v_mov_b32_dpp v142, v142 row_shr:1 row_mask:0xf bank_mask:0xf
	v_mov_b32_dpp v143, v143 row_shr:1 row_mask:0xf bank_mask:0xf
	v_pk_fma_f32 v[150:151], v[156:157], v[88:89], v[160:161]
	v_pk_mul_f32 v[138:139], v[134:135], v[178:179] op_sel_hi:[0,1]
	v_pk_fma_f32 v[142:143], v[146:147], v[142:143], v[150:151]
	v_pk_fma_f32 v[150:151], v[156:157], v[136:137], v[160:161]
	v_mov_b32_e32 v144, v88
	v_mov_b32_e32 v145, v89
	v_pk_fma_f32 v[88:89], v[146:147], v[88:89], v[150:151]
	v_mov_b32_e32 v84, v135
	v_pk_fma_f32 v[150:151], v[152:153], v[138:139], v[88:89]
	v_pk_fma_f32 v[88:89], v[156:157], v[138:139], v[160:161]
	v_pk_mul_f32 v[140:141], v[84:85], v[176:177] op_sel_hi:[0,1]
	v_pk_fma_f32 v[88:89], v[146:147], v[136:137], v[88:89]
	v_pk_fma_f32 v[142:143], v[152:153], v[136:137], v[142:143]
	v_pk_fma_f32 v[136:137], v[152:153], v[140:141], v[88:89]
	v_pk_fma_f32 v[88:89], v[156:157], v[140:141], v[160:161]
	v_pk_mul_f32 v[124:125], v[128:129], v[124:125] op_sel_hi:[0,1]
	v_pk_fma_f32 v[88:89], v[146:147], v[138:139], v[88:89]
	v_pk_mul_f32 v[120:121], v[128:129], v[120:121] op_sel:[1,0]
	v_pk_fma_f32 v[138:139], v[152:153], v[124:125], v[88:89]
	v_pk_fma_f32 v[88:89], v[156:157], v[124:125], v[160:161]
	v_pk_mul_f32 v[116:117], v[130:131], v[116:117] op_sel_hi:[0,1]
	v_pk_fma_f32 v[88:89], v[146:147], v[140:141], v[88:89]
	v_mov_b32_dpp v144, v144 row_shl:1 row_mask:0xf bank_mask:0xf
	v_pk_fma_f32 v[140:141], v[152:153], v[120:121], v[88:89]
	v_pk_fma_f32 v[88:89], v[156:157], v[120:121], v[160:161]
	v_mov_b32_dpp v145, v145 row_shl:1 row_mask:0xf bank_mask:0xf
	v_pk_fma_f32 v[88:89], v[146:147], v[124:125], v[88:89]
	s_mov_b32 s8, 0x3856241d
	v_pk_fma_f32 v[124:125], v[152:153], v[116:117], v[88:89]
	v_pk_fma_f32 v[88:89], v[156:157], v[116:117], v[160:161]
	v_and_b32_e32 v169, 0x7fffffff, v151
	v_pk_fma_f32 v[88:89], v[146:147], v[120:121], v[88:89]
	v_and_b32_e32 v168, 0x7fffffff, v150
	v_pk_fma_f32 v[120:121], v[152:153], v[112:113], v[88:89]
	v_pk_fma_f32 v[88:89], v[156:157], v[112:113], v[160:161]
	v_and_b32_e32 v167, 0x7fffffff, v137
	v_pk_fma_f32 v[88:89], v[146:147], v[116:117], v[88:89]
	v_and_b32_e32 v117, 0x7fffffff, v143
	v_pk_fma_f32 v[112:113], v[152:153], v[144:145], v[88:89]
	v_and_b32_e32 v116, 0x7fffffff, v142
	v_mov_b64_e32 v[88:89], s[8:9]
	v_pk_fma_f32 v[144:145], v[116:117], s[80:81], v[88:89] op_sel_hi:[1,0,0]
	v_pk_fma_f32 v[170:171], v[168:169], s[80:81], v[88:89] op_sel_hi:[1,0,0]
	v_pk_fma_f32 v[144:145], v[116:117], v[144:145], s[84:85] op_sel_hi:[1,1,0]
	v_pk_fma_f32 v[170:171], v[168:169], v[170:171], s[84:85] op_sel_hi:[1,1,0]
	v_pk_fma_f32 v[144:145], v[116:117], v[144:145], s[86:87] op_sel_hi:[1,1,0]
	v_pk_fma_f32 v[170:171], v[168:169], v[170:171], s[86:87] op_sel_hi:[1,1,0]
	v_pk_fma_f32 v[144:145], v[116:117], v[144:145], s[82:83] op_sel_hi:[1,1,0]
	v_and_b32_e32 v166, 0x7fffffff, v136
	v_pk_fma_f32 v[170:171], v[168:169], v[170:171], s[82:83] op_sel_hi:[1,1,0]
	v_pk_fma_f32 v[144:145], v[116:117], v[144:145], s[94:95] op_sel_hi:[1,1,0]
	v_and_b32_e32 v161, 0x7fffffff, v139
	v_and_b32_e32 v160, 0x7fffffff, v138
	v_pk_fma_f32 v[172:173], v[166:167], s[80:81], v[88:89] op_sel_hi:[1,0,0]
	v_pk_fma_f32 v[170:171], v[168:169], v[170:171], s[94:95] op_sel_hi:[1,1,0]
	v_pk_fma_f32 v[144:145], v[116:117], v[144:145], s[92:93] op_sel_hi:[1,1,0]
	v_pk_fma_f32 v[174:175], v[160:161], s[80:81], v[88:89] op_sel_hi:[1,0,0]
	v_pk_fma_f32 v[172:173], v[166:167], v[172:173], s[84:85] op_sel_hi:[1,1,0]
	v_pk_fma_f32 v[170:171], v[168:169], v[170:171], s[92:93] op_sel_hi:[1,1,0]
	v_pk_mul_f32 v[144:145], v[144:145], v[144:145]
	v_pk_fma_f32 v[174:175], v[160:161], v[174:175], s[84:85] op_sel_hi:[1,1,0]
	v_pk_fma_f32 v[172:173], v[166:167], v[172:173], s[86:87] op_sel_hi:[1,1,0]
	v_pk_mul_f32 v[170:171], v[170:171], v[170:171]
	v_pk_mul_f32 v[144:145], v[144:145], v[144:145]
	v_pk_fma_f32 v[174:175], v[160:161], v[174:175], s[86:87] op_sel_hi:[1,1,0]
	v_pk_fma_f32 v[172:173], v[166:167], v[172:173], s[82:83] op_sel_hi:[1,1,0]
	v_pk_mul_f32 v[170:171], v[170:171], v[170:171]
	v_pk_mul_f32 v[144:145], v[144:145], v[144:145]
	v_pk_fma_f32 v[174:175], v[160:161], v[174:175], s[82:83] op_sel_hi:[1,1,0]
	v_pk_fma_f32 v[172:173], v[166:167], v[172:173], s[94:95] op_sel_hi:[1,1,0]
	v_pk_mul_f32 v[170:171], v[170:171], v[170:171]
	v_pk_mul_f32 v[144:145], v[144:145], v[144:145]
	v_pk_fma_f32 v[174:175], v[160:161], v[174:175], s[94:95] op_sel_hi:[1,1,0]
	v_pk_fma_f32 v[172:173], v[166:167], v[172:173], s[92:93] op_sel_hi:[1,1,0]
	v_pk_mul_f32 v[170:171], v[170:171], v[170:171]
	v_rcp_f32_e32 v144, v144
	v_rcp_f32_e32 v145, v145
	v_pk_fma_f32 v[174:175], v[160:161], v[174:175], s[92:93] op_sel_hi:[1,1,0]
	v_pk_mul_f32 v[172:173], v[172:173], v[172:173]
	v_rcp_f32_e32 v170, v170
	v_rcp_f32_e32 v171, v171
	v_pk_mul_f32 v[174:175], v[174:175], v[174:175]
	v_pk_mul_f32 v[172:173], v[172:173], v[172:173]
	v_pk_mul_f32 v[174:175], v[174:175], v[174:175]
	v_pk_mul_f32 v[172:173], v[172:173], v[172:173]
	v_max_f32_e32 v143, 0, v143
	v_max_f32_e32 v142, 0, v142
	v_pk_mul_f32 v[174:175], v[174:175], v[174:175]
	v_pk_mul_f32 v[172:173], v[172:173], v[172:173]
	v_pk_fma_f32 v[116:117], v[116:117], v[144:145], v[142:143] neg_lo:[1,0,0] neg_hi:[1,0,0]
	v_max_f32_e32 v143, 0, v151
	v_max_f32_e32 v142, 0, v150
	v_pk_mul_f32 v[174:175], v[174:175], v[174:175]
	v_pk_fma_f32 v[168:169], v[168:169], v[170:171], v[142:143] neg_lo:[1,0,0] neg_hi:[1,0,0]
	v_rcp_f32_e32 v142, v172
	v_rcp_f32_e32 v143, v173
	v_rcp_f32_e32 v144, v174
	v_rcp_f32_e32 v145, v175
	v_max_f32_e32 v137, 0, v137
	v_max_f32_e32 v136, 0, v136
	v_pk_fma_f32 v[166:167], v[166:167], v[142:143], v[136:137] neg_lo:[1,0,0] neg_hi:[1,0,0]
	v_max_f32_e32 v137, 0, v139
	v_max_f32_e32 v136, 0, v138
	v_pk_fma_f32 v[160:161], v[160:161], v[144:145], v[136:137] neg_lo:[1,0,0] neg_hi:[1,0,0]
	v_and_b32_e32 v137, 0x7fffffff, v141
	v_and_b32_e32 v136, 0x7fffffff, v140
	v_pk_fma_f32 v[138:139], v[136:137], s[80:81], v[88:89] op_sel_hi:[1,0,0]
	v_and_b32_e32 v147, 0x7fffffff, v113
	v_pk_fma_f32 v[138:139], v[136:137], v[138:139], s[84:85] op_sel_hi:[1,1,0]
	v_and_b32_e32 v146, 0x7fffffff, v112
	v_pk_fma_f32 v[138:139], v[136:137], v[138:139], s[86:87] op_sel_hi:[1,1,0]
	v_and_b32_e32 v153, 0x7fffffff, v121
	v_and_b32_e32 v152, 0x7fffffff, v120
	v_and_b32_e32 v157, 0x7fffffff, v125
	v_and_b32_e32 v156, 0x7fffffff, v124
	v_pk_fma_f32 v[138:139], v[136:137], v[138:139], s[82:83] op_sel_hi:[1,1,0]
	v_pk_fma_f32 v[142:143], v[156:157], s[80:81], v[88:89] op_sel_hi:[1,0,0]
	v_pk_fma_f32 v[144:145], v[152:153], s[80:81], v[88:89] op_sel_hi:[1,0,0]
	v_pk_fma_f32 v[150:151], v[146:147], s[80:81], v[88:89] op_sel_hi:[1,0,0]
	v_pk_fma_f32 v[138:139], v[136:137], v[138:139], s[94:95] op_sel_hi:[1,1,0]
	v_pk_fma_f32 v[142:143], v[156:157], v[142:143], s[84:85] op_sel_hi:[1,1,0]
	v_pk_fma_f32 v[144:145], v[152:153], v[144:145], s[84:85] op_sel_hi:[1,1,0]
	v_pk_fma_f32 v[150:151], v[146:147], v[150:151], s[84:85] op_sel_hi:[1,1,0]
	v_pk_fma_f32 v[138:139], v[136:137], v[138:139], s[92:93] op_sel_hi:[1,1,0]
	v_pk_fma_f32 v[142:143], v[156:157], v[142:143], s[86:87] op_sel_hi:[1,1,0]
	v_pk_fma_f32 v[144:145], v[152:153], v[144:145], s[86:87] op_sel_hi:[1,1,0]
	v_pk_fma_f32 v[150:151], v[146:147], v[150:151], s[86:87] op_sel_hi:[1,1,0]
	v_pk_mul_f32 v[138:139], v[138:139], v[138:139]
	v_pk_fma_f32 v[142:143], v[156:157], v[142:143], s[82:83] op_sel_hi:[1,1,0]
	v_pk_fma_f32 v[144:145], v[152:153], v[144:145], s[82:83] op_sel_hi:[1,1,0]
	v_pk_fma_f32 v[150:151], v[146:147], v[150:151], s[82:83] op_sel_hi:[1,1,0]
	v_pk_mul_f32 v[138:139], v[138:139], v[138:139]
	v_pk_fma_f32 v[142:143], v[156:157], v[142:143], s[94:95] op_sel_hi:[1,1,0]
	v_pk_fma_f32 v[144:145], v[152:153], v[144:145], s[94:95] op_sel_hi:[1,1,0]
	v_pk_fma_f32 v[150:151], v[146:147], v[150:151], s[94:95] op_sel_hi:[1,1,0]
	v_pk_mul_f32 v[138:139], v[138:139], v[138:139]
	v_pk_fma_f32 v[142:143], v[156:157], v[142:143], s[92:93] op_sel_hi:[1,1,0]
	v_pk_fma_f32 v[144:145], v[152:153], v[144:145], s[92:93] op_sel_hi:[1,1,0]
	v_pk_fma_f32 v[150:151], v[146:147], v[150:151], s[92:93] op_sel_hi:[1,1,0]
	v_pk_mul_f32 v[138:139], v[138:139], v[138:139]
	v_pk_mul_f32 v[142:143], v[142:143], v[142:143]
	v_pk_mul_f32 v[144:145], v[144:145], v[144:145]
	v_pk_mul_f32 v[150:151], v[150:151], v[150:151]
	v_rcp_f32_e32 v138, v138
	v_rcp_f32_e32 v139, v139
	v_pk_mul_f32 v[142:143], v[142:143], v[142:143]
	v_pk_mul_f32 v[144:145], v[144:145], v[144:145]
	v_pk_mul_f32 v[150:151], v[150:151], v[150:151]
	v_pk_mul_f32 v[142:143], v[142:143], v[142:143]
	v_pk_mul_f32 v[144:145], v[144:145], v[144:145]
	v_pk_mul_f32 v[150:151], v[150:151], v[150:151]
	v_pk_mul_f32 v[142:143], v[142:143], v[142:143]
	v_pk_mul_f32 v[144:145], v[144:145], v[144:145]
	v_pk_mul_f32 v[150:151], v[150:151], v[150:151]
	v_max_f32_e32 v141, 0, v141
	v_max_f32_e32 v140, 0, v140
	v_rcp_f32_e32 v142, v142
	v_rcp_f32_e32 v143, v143
	v_pk_fma_f32 v[170:171], v[136:137], v[138:139], v[140:141] neg_lo:[1,0,0] neg_hi:[1,0,0]
	v_rcp_f32_e32 v136, v144
	v_rcp_f32_e32 v137, v145
	v_rcp_f32_e32 v138, v150
	v_rcp_f32_e32 v139, v151
	v_max_f32_e32 v125, 0, v125
	v_max_f32_e32 v124, 0, v124
	v_max_f32_e32 v121, 0, v121
	v_max_f32_e32 v120, 0, v120
	v_max_f32_e32 v113, 0, v113
	v_max_f32_e32 v112, 0, v112
	v_pk_fma_f32 v[124:125], v[156:157], v[142:143], v[124:125] neg_lo:[1,0,0] neg_hi:[1,0,0]
	v_pk_fma_f32 v[120:121], v[152:153], v[136:137], v[120:121] neg_lo:[1,0,0] neg_hi:[1,0,0]
	v_pk_fma_f32 v[112:113], v[146:147], v[138:139], v[112:113] neg_lo:[1,0,0] neg_hi:[1,0,0]
	ds_read2_b64 v[136:139], v92 offset0:128 offset1:129
	ds_read2_b64 v[140:143], v92 offset0:192 offset1:193
	ds_read2_b64 v[144:147], v92 offset0:64 offset1:65
	ds_read2_b64 v[150:153], v92 offset1:1
	v_pk_mul_f32 v[176:177], v[80:81], v[64:65] op_sel_hi:[0,1]
	v_pk_mul_f32 v[108:109], v[132:133], v[108:109] op_sel_hi:[0,1]
	v_mov_b32_e32 v64, v176
	v_mov_b32_e32 v65, v177
	v_pk_mul_f32 v[174:175], v[130:131], v[68:69] op_sel_hi:[0,1]
	v_mov_b32_dpp v64, v64 row_shr:1 row_mask:0xf bank_mask:0xf
	v_mov_b32_dpp v65, v65 row_shr:1 row_mask:0xf bank_mask:0xf
	s_waitcnt lgkmcnt(0)
	v_pk_fma_f32 v[68:69], v[144:145], v[108:109], v[140:141]
	v_pk_mul_f32 v[104:105], v[132:133], v[104:105] op_sel:[1,0]
	v_pk_fma_f32 v[64:65], v[150:151], v[64:65], v[68:69]
	v_pk_mul_f32 v[156:157], v[128:129], v[76:77] op_sel_hi:[0,1]
	v_pk_fma_f32 v[64:65], v[136:137], v[104:105], v[64:65]
	v_pk_mul_f32 v[100:101], v[134:135], v[100:101] op_sel_hi:[0,1]
	v_pk_mul_f32 v[64:65], v[64:65], v[116:117]
	v_pk_mul_f32 v[96:97], v[84:85], v[96:97] op_sel_hi:[0,1]
	v_cvt_pk_fp8_f32 v77, v64, v65
	s_nop 0
	v_pk_fma_f32 v[64:65], v[144:145], v[104:105], v[140:141]
	v_pk_mul_f32 v[172:173], v[128:129], v[72:73] op_sel:[1,0]
	v_pk_fma_f32 v[64:65], v[150:151], v[108:109], v[64:65]
	v_mov_b32_e32 v178, v108
	v_pk_fma_f32 v[64:65], v[136:137], v[100:101], v[64:65]
	v_mov_b32_e32 v179, v109
	v_pk_mul_f32 v[64:65], v[64:65], v[168:169]
	v_mov_b32_dpp v178, v178 row_shl:1 row_mask:0xf bank_mask:0xf
	v_cvt_pk_fp8_f32 v76, v64, v65
	s_nop 0
	v_pk_fma_f32 v[64:65], v[144:145], v[100:101], v[140:141]
	v_mov_b32_dpp v179, v179 row_shl:1 row_mask:0xf bank_mask:0xf
	v_pk_fma_f32 v[64:65], v[150:151], v[104:105], v[64:65]
	v_cvt_f32_i32_e32 v103, v103
	v_pk_fma_f32 v[64:65], v[136:137], v[96:97], v[64:65]
	v_cvt_f32_i32_e32 v102, v102
	v_pk_mul_f32 v[64:65], v[64:65], v[166:167]
	v_cvt_f32_i32_e32 v99, v99
	v_cvt_pk_fp8_f32 v73, v64, v65
	s_nop 0
	v_pk_fma_f32 v[64:65], v[144:145], v[96:97], v[140:141]
	v_cvt_f32_i32_e32 v98, v98
	v_pk_fma_f32 v[64:65], v[150:151], v[100:101], v[64:65]
	v_cvt_f32_i32_e32 v101, v107
	v_pk_fma_f32 v[64:65], v[136:137], v[156:157], v[64:65]
	v_cvt_f32_i32_e32 v100, v106
	v_pk_mul_f32 v[64:65], v[64:65], v[160:161]
	v_cvt_f32_i32_e32 v105, v127
	v_cvt_pk_fp8_f32 v72, v64, v65
	s_nop 0
	v_pk_fma_f32 v[64:65], v[144:145], v[156:157], v[140:141]
	v_cvt_f32_i32_e32 v104, v126
	v_pk_fma_f32 v[64:65], v[150:151], v[96:97], v[64:65]
	v_pk_fma_f32 v[96:97], v[144:145], v[176:177], v[140:141]
	v_pk_fma_f32 v[64:65], v[136:137], v[172:173], v[64:65]
	v_pk_fma_f32 v[96:97], v[150:151], v[174:175], v[96:97]
	v_pk_mul_f32 v[64:65], v[64:65], v[170:171]
	v_pk_fma_f32 v[96:97], v[136:137], v[178:179], v[96:97]
	v_cvt_pk_fp8_f32 v69, v64, v65
	s_nop 0
	v_pk_fma_f32 v[64:65], v[144:145], v[172:173], v[140:141]
	v_pk_mul_f32 v[96:97], v[96:97], v[112:113]
	v_pk_fma_f32 v[64:65], v[150:151], v[156:157], v[64:65]
	v_pk_mul_f32 v[100:101], v[132:133], v[100:101] op_sel:[1,0]
	v_pk_fma_f32 v[64:65], v[136:137], v[174:175], v[64:65]
	v_cvt_f32_i32_e32 v107, v123
	v_pk_mul_f32 v[64:65], v[64:65], v[124:125]
	v_cvt_f32_i32_e32 v106, v122
	v_cvt_pk_fp8_f32 v68, v64, v65
	s_nop 0
	v_pk_fma_f32 v[64:65], v[144:145], v[174:175], v[140:141]
	v_pk_mul_f32 v[102:103], v[134:135], v[102:103] op_sel_hi:[0,1]
	v_pk_fma_f32 v[64:65], v[150:151], v[172:173], v[64:65]
	v_cvt_f32_i32_e32 v109, v119
	v_pk_fma_f32 v[64:65], v[136:137], v[176:177], v[64:65]
	v_cvt_f32_i32_e32 v108, v118
	v_pk_mul_f32 v[64:65], v[64:65], v[120:121]
	v_pk_mul_f32 v[98:99], v[84:85], v[98:99] op_sel_hi:[0,1]
	v_cvt_pk_fp8_f32 v65, v64, v65
	s_nop 0
	v_cvt_pk_fp8_f32 v64, v96, v97
	s_nop 0
	v_cvt_f32_i32_e32 v97, v111
	v_cvt_f32_i32_e32 v96, v110
	v_cvt_f32_i32_e32 v111, v115
	v_cvt_f32_i32_e32 v110, v114
	v_pk_mul_f32 v[104:105], v[128:129], v[104:105] op_sel_hi:[0,1]
	v_pk_mul_f32 v[96:97], v[132:133], v[96:97] op_sel_hi:[0,1]
	v_pk_fma_f32 v[116:117], v[158:159], v[96:97], v[162:163]
	v_pk_mul_f32 v[110:111], v[80:81], v[110:111] op_sel_hi:[0,1]
	v_mov_b32_e32 v112, v110
	v_mov_b32_e32 v113, v111
	v_mov_b32_e32 v114, v96
	v_mov_b32_dpp v112, v112 row_shr:1 row_mask:0xf bank_mask:0xf
	v_mov_b32_dpp v113, v113 row_shr:1 row_mask:0xf bank_mask:0xf
	v_pk_fma_f32 v[112:113], v[148:149], v[112:113], v[116:117]
	v_pk_fma_f32 v[116:117], v[158:159], v[100:101], v[162:163]
	v_mov_b32_e32 v115, v97
	v_pk_fma_f32 v[96:97], v[148:149], v[96:97], v[116:117]
	v_pk_fma_f32 v[116:117], v[158:159], v[102:103], v[162:163]
	v_pk_fma_f32 v[112:113], v[154:155], v[100:101], v[112:113]
	v_pk_fma_f32 v[100:101], v[148:149], v[100:101], v[116:117]
	v_pk_fma_f32 v[116:117], v[158:159], v[98:99], v[162:163]
	v_pk_mul_f32 v[106:107], v[128:129], v[106:107] op_sel:[1,0]
	v_pk_fma_f32 v[96:97], v[154:155], v[102:103], v[96:97]
	v_pk_fma_f32 v[102:103], v[148:149], v[102:103], v[116:117]
	v_pk_fma_f32 v[116:117], v[158:159], v[104:105], v[162:163]
	v_pk_mul_f32 v[108:109], v[130:131], v[108:109] op_sel_hi:[0,1]
	v_pk_fma_f32 v[100:101], v[154:155], v[98:99], v[100:101]
	v_pk_fma_f32 v[98:99], v[148:149], v[98:99], v[116:117]
	v_pk_fma_f32 v[116:117], v[158:159], v[106:107], v[162:163]
	v_pk_fma_f32 v[102:103], v[154:155], v[104:105], v[102:103]
	v_pk_fma_f32 v[104:105], v[148:149], v[104:105], v[116:117]
	v_pk_fma_f32 v[116:117], v[158:159], v[108:109], v[162:163]
	v_pk_fma_f32 v[98:99], v[154:155], v[106:107], v[98:99]
	v_pk_fma_f32 v[106:107], v[148:149], v[106:107], v[116:117]
	v_mov_b32_dpp v114, v114 row_shl:1 row_mask:0xf bank_mask:0xf
	v_pk_fma_f32 v[106:107], v[154:155], v[110:111], v[106:107]
	v_pk_fma_f32 v[110:111], v[158:159], v[110:111], v[162:163]
	v_mov_b32_dpp v115, v115 row_shl:1 row_mask:0xf bank_mask:0xf
	v_pk_fma_f32 v[104:105], v[154:155], v[108:109], v[104:105]
	v_pk_fma_f32 v[108:109], v[148:149], v[108:109], v[110:111]
	v_and_b32_e32 v111, 0x7fffffff, v113
	v_and_b32_e32 v110, 0x7fffffff, v112
	v_pk_fma_f32 v[108:109], v[154:155], v[114:115], v[108:109]
	v_pk_fma_f32 v[114:115], v[110:111], s[80:81], v[88:89] op_sel_hi:[1,0,0]
	v_and_b32_e32 v125, 0x7fffffff, v101
	v_pk_fma_f32 v[114:115], v[110:111], v[114:115], s[84:85] op_sel_hi:[1,1,0]
	v_and_b32_e32 v124, 0x7fffffff, v100
	v_pk_fma_f32 v[114:115], v[110:111], v[114:115], s[86:87] op_sel_hi:[1,1,0]
	v_and_b32_e32 v123, 0x7fffffff, v103
	v_pk_fma_f32 v[114:115], v[110:111], v[114:115], s[82:83] op_sel_hi:[1,1,0]
	v_and_b32_e32 v122, 0x7fffffff, v102
	v_pk_fma_f32 v[140:141], v[124:125], s[80:81], v[88:89] op_sel_hi:[1,0,0]
	v_pk_fma_f32 v[114:115], v[110:111], v[114:115], s[94:95] op_sel_hi:[1,1,0]
	v_pk_fma_f32 v[144:145], v[122:123], s[80:81], v[88:89] op_sel_hi:[1,0,0]
	v_pk_fma_f32 v[140:141], v[124:125], v[140:141], s[84:85] op_sel_hi:[1,1,0]
	v_pk_fma_f32 v[114:115], v[110:111], v[114:115], s[92:93] op_sel_hi:[1,1,0]
	v_pk_fma_f32 v[144:145], v[122:123], v[144:145], s[84:85] op_sel_hi:[1,1,0]
	v_pk_fma_f32 v[140:141], v[124:125], v[140:141], s[86:87] op_sel_hi:[1,1,0]
	v_pk_mul_f32 v[114:115], v[114:115], v[114:115]
	v_pk_fma_f32 v[144:145], v[122:123], v[144:145], s[86:87] op_sel_hi:[1,1,0]
	v_pk_fma_f32 v[140:141], v[124:125], v[140:141], s[82:83] op_sel_hi:[1,1,0]
	v_pk_mul_f32 v[114:115], v[114:115], v[114:115]
	v_pk_fma_f32 v[144:145], v[122:123], v[144:145], s[82:83] op_sel_hi:[1,1,0]
	v_pk_fma_f32 v[140:141], v[124:125], v[140:141], s[94:95] op_sel_hi:[1,1,0]
	v_pk_mul_f32 v[114:115], v[114:115], v[114:115]
	v_pk_fma_f32 v[144:145], v[122:123], v[144:145], s[94:95] op_sel_hi:[1,1,0]
	v_pk_fma_f32 v[140:141], v[124:125], v[140:141], s[92:93] op_sel_hi:[1,1,0]
	v_pk_mul_f32 v[114:115], v[114:115], v[114:115]
	v_pk_fma_f32 v[144:145], v[122:123], v[144:145], s[92:93] op_sel_hi:[1,1,0]
	v_pk_mul_f32 v[140:141], v[140:141], v[140:141]
	v_rcp_f32_e32 v114, v114
	v_rcp_f32_e32 v115, v115
	v_pk_mul_f32 v[144:145], v[144:145], v[144:145]
	v_pk_mul_f32 v[140:141], v[140:141], v[140:141]
	v_pk_mul_f32 v[144:145], v[144:145], v[144:145]
	v_pk_mul_f32 v[140:141], v[140:141], v[140:141]
	v_pk_mul_f32 v[144:145], v[144:145], v[144:145]
	v_pk_mul_f32 v[140:141], v[140:141], v[140:141]
	v_max_f32_e32 v113, 0, v113
	v_max_f32_e32 v112, 0, v112
	v_pk_mul_f32 v[144:145], v[144:145], v[144:145]
	v_pk_fma_f32 v[110:111], v[110:111], v[114:115], v[112:113] neg_lo:[1,0,0] neg_hi:[1,0,0]
	v_rcp_f32_e32 v112, v140
	v_rcp_f32_e32 v113, v141
	v_rcp_f32_e32 v114, v144
	v_rcp_f32_e32 v115, v145
	v_max_f32_e32 v101, 0, v101
	v_max_f32_e32 v100, 0, v100
	v_and_b32_e32 v117, 0x7fffffff, v109
	v_and_b32_e32 v116, 0x7fffffff, v108
	v_and_b32_e32 v119, 0x7fffffff, v107
	v_and_b32_e32 v118, 0x7fffffff, v106
	v_and_b32_e32 v121, 0x7fffffff, v105
	v_and_b32_e32 v120, 0x7fffffff, v104
	v_and_b32_e32 v127, 0x7fffffff, v97
	v_and_b32_e32 v126, 0x7fffffff, v96
	v_pk_fma_f32 v[100:101], v[124:125], v[112:113], v[100:101] neg_lo:[1,0,0] neg_hi:[1,0,0]
	v_max_f32_e32 v103, 0, v103
	v_max_f32_e32 v102, 0, v102
	v_and_b32_e32 v113, 0x7fffffff, v99
	v_and_b32_e32 v112, 0x7fffffff, v98
	v_pk_fma_f32 v[136:137], v[126:127], s[80:81], v[88:89] op_sel_hi:[1,0,0]
	v_pk_fma_f32 v[102:103], v[122:123], v[114:115], v[102:103] neg_lo:[1,0,0] neg_hi:[1,0,0]
	v_pk_fma_f32 v[114:115], v[112:113], s[80:81], v[88:89] op_sel_hi:[1,0,0]
	v_pk_fma_f32 v[122:123], v[120:121], s[80:81], v[88:89] op_sel_hi:[1,0,0]
	v_pk_fma_f32 v[124:125], v[118:119], s[80:81], v[88:89] op_sel_hi:[1,0,0]
	v_pk_fma_f32 v[88:89], v[116:117], s[80:81], v[88:89] op_sel_hi:[1,0,0]
	v_pk_fma_f32 v[114:115], v[112:113], v[114:115], s[84:85] op_sel_hi:[1,1,0]
	v_pk_fma_f32 v[88:89], v[116:117], v[88:89], s[84:85] op_sel_hi:[1,1,0]
	v_pk_fma_f32 v[114:115], v[112:113], v[114:115], s[86:87] op_sel_hi:[1,1,0]
	v_pk_fma_f32 v[88:89], v[116:117], v[88:89], s[86:87] op_sel_hi:[1,1,0]
	v_pk_fma_f32 v[114:115], v[112:113], v[114:115], s[82:83] op_sel_hi:[1,1,0]
	v_pk_fma_f32 v[88:89], v[116:117], v[88:89], s[82:83] op_sel_hi:[1,1,0]
	v_pk_fma_f32 v[114:115], v[112:113], v[114:115], s[94:95] op_sel_hi:[1,1,0]
	v_pk_fma_f32 v[88:89], v[116:117], v[88:89], s[94:95] op_sel_hi:[1,1,0]
	v_pk_fma_f32 v[114:115], v[112:113], v[114:115], s[92:93] op_sel_hi:[1,1,0]
	v_pk_fma_f32 v[88:89], v[116:117], v[88:89], s[92:93] op_sel_hi:[1,1,0]
	v_pk_fma_f32 v[124:125], v[118:119], v[124:125], s[84:85] op_sel_hi:[1,1,0]
	v_pk_mul_f32 v[88:89], v[88:89], v[88:89]
	v_pk_mul_f32 v[114:115], v[114:115], v[114:115]
	v_pk_mul_f32 v[88:89], v[88:89], v[88:89]
	v_pk_fma_f32 v[136:137], v[126:127], v[136:137], s[84:85] op_sel_hi:[1,1,0]
	v_pk_fma_f32 v[124:125], v[118:119], v[124:125], s[86:87] op_sel_hi:[1,1,0]
	v_pk_mul_f32 v[114:115], v[114:115], v[114:115]
	v_pk_mul_f32 v[88:89], v[88:89], v[88:89]
	v_pk_fma_f32 v[136:137], v[126:127], v[136:137], s[86:87] op_sel_hi:[1,1,0]
	v_pk_fma_f32 v[124:125], v[118:119], v[124:125], s[82:83] op_sel_hi:[1,1,0]
	v_pk_mul_f32 v[114:115], v[114:115], v[114:115]
	v_pk_mul_f32 v[88:89], v[88:89], v[88:89]
	v_cvt_f32_i32_e32 v83, v83
	v_cvt_f32_i32_e32 v82, v82
	v_pk_fma_f32 v[136:137], v[126:127], v[136:137], s[82:83] op_sel_hi:[1,1,0]
	v_pk_fma_f32 v[124:125], v[118:119], v[124:125], s[94:95] op_sel_hi:[1,1,0]
	v_pk_mul_f32 v[114:115], v[114:115], v[114:115]
	v_rcp_f32_e32 v88, v88
	v_rcp_f32_e32 v89, v89
	v_cvt_f32_i32_e32 v79, v79
	v_cvt_f32_i32_e32 v78, v78
	v_pk_fma_f32 v[136:137], v[126:127], v[136:137], s[94:95] op_sel_hi:[1,1,0]
	v_pk_fma_f32 v[124:125], v[118:119], v[124:125], s[92:93] op_sel_hi:[1,1,0]
	v_rcp_f32_e32 v114, v114
	v_rcp_f32_e32 v115, v115
	v_pk_fma_f32 v[136:137], v[126:127], v[136:137], s[92:93] op_sel_hi:[1,1,0]
	v_pk_mul_f32 v[124:125], v[124:125], v[124:125]
	v_cvt_f32_i32_e32 v75, v75
	v_cvt_f32_i32_e32 v74, v74
	v_pk_mul_f32 v[136:137], v[136:137], v[136:137]
	v_pk_mul_f32 v[124:125], v[124:125], v[124:125]
	v_max_f32_e32 v109, 0, v109
	v_max_f32_e32 v108, 0, v108
	v_pk_mul_f32 v[82:83], v[80:81], v[82:83] op_sel_hi:[0,1]
	v_pk_mul_f32 v[136:137], v[136:137], v[136:137]
	v_pk_mul_f32 v[124:125], v[124:125], v[124:125]
	v_max_f32_e32 v99, 0, v99
	v_max_f32_e32 v98, 0, v98
	v_pk_fma_f32 v[88:89], v[116:117], v[88:89], v[108:109] neg_lo:[1,0,0] neg_hi:[1,0,0]
	v_pk_mul_f32 v[78:79], v[132:133], v[78:79] op_sel_hi:[0,1]
	v_mov_b32_e32 v108, v82
	v_mov_b32_e32 v109, v83
	v_pk_mul_f32 v[136:137], v[136:137], v[136:137]
	v_pk_mul_f32 v[124:125], v[124:125], v[124:125]
	v_pk_fma_f32 v[98:99], v[112:113], v[114:115], v[98:99] neg_lo:[1,0,0] neg_hi:[1,0,0]
	v_mov_b32_dpp v108, v108 row_shr:1 row_mask:0xf bank_mask:0xf
	v_mov_b32_dpp v109, v109 row_shr:1 row_mask:0xf bank_mask:0xf
	v_pk_fma_f32 v[114:115], v[146:147], v[78:79], v[142:143]
	v_pk_mul_f32 v[136:137], v[136:137], v[136:137]
	v_rcp_f32_e32 v112, v124
	v_rcp_f32_e32 v113, v125
	v_cvt_f32_i32_e32 v71, v71
	v_cvt_f32_i32_e32 v70, v70
	v_pk_mul_f32 v[74:75], v[132:133], v[74:75] op_sel:[1,0]
	v_pk_fma_f32 v[108:109], v[152:153], v[108:109], v[114:115]
	v_rcp_f32_e32 v136, v136
	v_rcp_f32_e32 v137, v137
	v_pk_fma_f32 v[108:109], v[138:139], v[74:75], v[108:109]
	v_max_f32_e32 v107, 0, v107
	v_pk_mul_f32 v[108:109], v[108:109], v[110:111]
	v_max_f32_e32 v106, 0, v106
	v_cvt_pk_fp8_f32 v77, v108, v109 op_sel:[0,0,1]
	s_nop 0
	v_pk_fma_f32 v[108:109], v[146:147], v[74:75], v[142:143]
	v_max_f32_e32 v97, 0, v97
	v_max_f32_e32 v96, 0, v96
	v_pk_fma_f32 v[106:107], v[118:119], v[112:113], v[106:107] neg_lo:[1,0,0] neg_hi:[1,0,0]
	v_cvt_f32_i32_e32 v67, v67
	v_cvt_f32_i32_e32 v66, v66
	v_pk_mul_f32 v[70:71], v[134:135], v[70:71] op_sel_hi:[0,1]
	v_mov_b32_e32 v112, v78
	v_mov_b32_e32 v113, v79
	v_pk_fma_f32 v[78:79], v[152:153], v[78:79], v[108:109]
	v_pk_fma_f32 v[96:97], v[126:127], v[136:137], v[96:97] neg_lo:[1,0,0] neg_hi:[1,0,0]
	v_pk_fma_f32 v[78:79], v[138:139], v[70:71], v[78:79]
	v_pk_fma_f32 v[122:123], v[120:121], v[122:123], s[84:85] op_sel_hi:[1,1,0]
	v_pk_mul_f32 v[78:79], v[78:79], v[96:97]
	v_pk_mul_f32 v[66:67], v[84:85], v[66:67] op_sel_hi:[0,1]
	v_cvt_pk_fp8_f32 v76, v78, v79 op_sel:[0,0,1]
	s_nop 0
	v_pk_fma_f32 v[78:79], v[146:147], v[70:71], v[142:143]
	v_cvt_f32_i32_e32 v95, v95
	v_cvt_f32_i32_e32 v94, v94
	v_pk_fma_f32 v[74:75], v[152:153], v[74:75], v[78:79]
	v_pk_fma_f32 v[122:123], v[120:121], v[122:123], s[86:87] op_sel_hi:[1,1,0]
	v_pk_fma_f32 v[74:75], v[138:139], v[66:67], v[74:75]
	v_pk_fma_f32 v[122:123], v[120:121], v[122:123], s[82:83] op_sel_hi:[1,1,0]
	v_pk_mul_f32 v[74:75], v[74:75], v[100:101]
	v_pk_fma_f32 v[122:123], v[120:121], v[122:123], s[94:95] op_sel_hi:[1,1,0]
	v_cvt_pk_fp8_f32 v73, v74, v75 op_sel:[0,0,1]
	s_nop 0
	v_pk_fma_f32 v[74:75], v[146:147], v[66:67], v[142:143]
	v_pk_fma_f32 v[122:123], v[120:121], v[122:123], s[92:93] op_sel_hi:[1,1,0]
	v_cvt_f32_i32_e32 v91, v91
	v_cvt_f32_i32_e32 v90, v90
	v_pk_mul_f32 v[94:95], v[128:129], v[94:95] op_sel_hi:[0,1]
	v_pk_fma_f32 v[70:71], v[152:153], v[70:71], v[74:75]
	v_pk_mul_f32 v[122:123], v[122:123], v[122:123]
	v_pk_fma_f32 v[70:71], v[138:139], v[94:95], v[70:71]
	v_pk_mul_f32 v[122:123], v[122:123], v[122:123]
	v_pk_mul_f32 v[70:71], v[70:71], v[102:103]
	v_pk_mul_f32 v[122:123], v[122:123], v[122:123]
	v_cvt_pk_fp8_f32 v72, v70, v71 op_sel:[0,0,1]
	s_nop 0
	v_pk_fma_f32 v[70:71], v[146:147], v[94:95], v[142:143]
	v_pk_mul_f32 v[122:123], v[122:123], v[122:123]
	v_cvt_f32_i32_e32 v87, v87
	v_cvt_f32_i32_e32 v86, v86
	v_pk_mul_f32 v[90:91], v[128:129], v[90:91] op_sel:[1,0]
	v_pk_fma_f32 v[66:67], v[152:153], v[66:67], v[70:71]
	v_rcp_f32_e32 v122, v122
	v_rcp_f32_e32 v123, v123
	v_pk_fma_f32 v[66:67], v[138:139], v[90:91], v[66:67]
	v_max_f32_e32 v105, 0, v105
	v_pk_mul_f32 v[66:67], v[66:67], v[98:99]
	v_max_f32_e32 v104, 0, v104
	v_cvt_pk_fp8_f32 v69, v66, v67 op_sel:[0,0,1]
	s_nop 0
	v_pk_fma_f32 v[66:67], v[146:147], v[90:91], v[142:143]
	v_pk_mul_f32 v[86:87], v[130:131], v[86:87] op_sel_hi:[0,1]
	v_pk_fma_f32 v[66:67], v[152:153], v[94:95], v[66:67]
	v_pk_fma_f32 v[104:105], v[120:121], v[122:123], v[104:105] neg_lo:[1,0,0] neg_hi:[1,0,0]
	v_pk_fma_f32 v[66:67], v[138:139], v[86:87], v[66:67]
	v_mov_b32_dpp v112, v112 row_shl:1 row_mask:0xf bank_mask:0xf
	v_pk_mul_f32 v[66:67], v[66:67], v[104:105]
	v_mov_b32_dpp v113, v113 row_shl:1 row_mask:0xf bank_mask:0xf
	v_cvt_pk_fp8_f32 v68, v66, v67 op_sel:[0,0,1]
	s_nop 0
	v_pk_fma_f32 v[66:67], v[146:147], v[86:87], v[142:143]
	s_waitcnt vmcnt(0)
	v_add_u32_e32 v102, s37, v81
	v_pk_fma_f32 v[66:67], v[152:153], v[90:91], v[66:67]
	s_movk_i32 s3, 0x4000
	v_pk_fma_f32 v[66:67], v[138:139], v[82:83], v[66:67]
	v_cmp_gt_i32_e64 s[8:9], s3, v102
	v_pk_mul_f32 v[66:67], v[66:67], v[106:107]
	s_nop 0
	v_cvt_pk_fp8_f32 v65, v66, v67 op_sel:[0,0,1]
	s_nop 0
	v_pk_fma_f32 v[66:67], v[146:147], v[82:83], v[142:143]
	s_nop 0
	v_pk_fma_f32 v[66:67], v[152:153], v[86:87], v[66:67]
	s_nop 0
	v_pk_fma_f32 v[66:67], v[138:139], v[112:113], v[66:67]
	s_nop 0
	v_pk_mul_f32 v[66:67], v[66:67], v[88:89]
	s_nop 0
	v_cvt_pk_fp8_f32 v64, v66, v67 op_sel:[0,0,1]
	s_nop 0
	v_add_u32_e32 v66, -1, v81
	v_cmp_gt_u32_e32 vcc, s87, v66
	s_and_b64 s[10:11], vcc, s[8:9]
	s_and_saveexec_b64 s[8:9], s[10:11]
	s_cbranch_execz .LBB0_688
	s_movk_i32 s12, 0xb00
	v_mad_u64_u32 v[66:67], s[12:13], v102, s12, v[164:165]
	buffer_store_dword v77, v66, s[88:91], 0 offen sc1
.LBB0_688:
	s_or_b64 exec, exec, s[8:9]
	v_or_b32_e32 v66, 1, v81
	v_add_u32_e32 v103, s37, v66
	v_cmp_gt_u32_e32 vcc, s87, v81
	v_cmp_gt_i32_e64 s[8:9], s3, v103
	s_and_b64 s[12:13], vcc, s[8:9]
	s_and_saveexec_b64 s[8:9], s[12:13]
	s_cbranch_execz .LBB0_690
	s_movk_i32 s14, 0xb00
	v_mad_u64_u32 v[66:67], s[14:15], v103, s14, v[164:165]
	buffer_store_dword v76, v66, s[88:91], 0 offen sc1
.LBB0_690:
	s_or_b64 exec, exec, s[8:9]
	v_or_b32_e32 v66, 2, v81
	v_add_u32_e32 v104, s37, v66
	v_cmp_gt_i32_e64 s[8:9], s3, v104
	s_and_b64 s[14:15], vcc, s[8:9]
	s_and_saveexec_b64 s[8:9], s[14:15]
	s_cbranch_execz .LBB0_692
	s_movk_i32 s16, 0xb00
	v_mad_u64_u32 v[70:71], s[16:17], v104, s16, v[164:165]
	buffer_store_dword v73, v70, s[88:91], 0 offen sc1
.LBB0_692:
	s_or_b64 exec, exec, s[8:9]
	v_or_b32_e32 v67, 3, v81
	v_add_u32_e32 v105, s37, v67
	v_cmp_gt_u32_e32 vcc, s87, v66
	v_cmp_gt_i32_e64 s[8:9], s3, v105
	s_and_b64 s[16:17], vcc, s[8:9]
	s_and_saveexec_b64 s[8:9], s[16:17]
	s_cbranch_execz .LBB0_694
	s_movk_i32 s18, 0xb00
	v_mad_u64_u32 v[66:67], s[18:19], v105, s18, v[164:165]
	buffer_store_dword v72, v66, s[88:91], 0 offen sc1
.LBB0_694:
	s_or_b64 exec, exec, s[8:9]
	v_or_b32_e32 v66, 4, v81
	v_add_u32_e32 v106, s37, v66
	v_cmp_gt_i32_e64 s[8:9], s3, v106
	s_and_b64 s[18:19], vcc, s[8:9]
	s_and_saveexec_b64 s[8:9], s[18:19]
	s_cbranch_execz .LBB0_696
	s_movk_i32 s20, 0xb00
	v_mad_u64_u32 v[70:71], s[20:21], v106, s20, v[164:165]
	buffer_store_dword v69, v70, s[88:91], 0 offen sc1
.LBB0_696:
	s_or_b64 exec, exec, s[8:9]
	v_or_b32_e32 v67, 5, v81
	v_add_u32_e32 v107, s37, v67
	v_cmp_gt_u32_e32 vcc, s87, v66
	v_cmp_gt_i32_e64 s[8:9], s3, v107
	s_and_b64 s[20:21], vcc, s[8:9]
	s_and_saveexec_b64 s[8:9], s[20:21]
	s_cbranch_execz .LBB0_698
	s_movk_i32 s22, 0xb00
	v_mad_u64_u32 v[66:67], s[22:23], v107, s22, v[164:165]
	buffer_store_dword v68, v66, s[88:91], 0 offen sc1
.LBB0_698:
	s_or_b64 exec, exec, s[8:9]
	v_or_b32_e32 v66, 6, v81
	v_add_u32_e32 v108, s37, v66
	v_cmp_gt_i32_e64 s[8:9], s3, v108
	s_and_b64 s[22:23], vcc, s[8:9]
	s_and_saveexec_b64 s[8:9], s[22:23]
	s_cbranch_execz .LBB0_700
	s_movk_i32 s24, 0xb00
	v_mad_u64_u32 v[66:67], s[24:25], v108, s24, v[164:165]
	buffer_store_dword v65, v66, s[88:91], 0 offen sc1
.LBB0_700:
	s_or_b64 exec, exec, s[8:9]
	v_or_b32_e32 v65, 7, v81
	v_add_u32_e32 v203, s37, v65
	s_movk_i32 s8, 0x7f
	v_cmp_gt_u32_e32 vcc, s8, v65
	v_cmp_gt_i32_e64 s[8:9], s3, v203
	s_and_b64 s[24:25], vcc, s[8:9]
	s_and_saveexec_b64 s[8:9], s[24:25]
	s_cbranch_execz .LBB0_702
	s_movk_i32 s3, 0xb00
	v_mad_u64_u32 v[66:67], s[42:43], v203, s3, v[164:165]
	buffer_store_dword v64, v66, s[88:91], 0 offen sc1

.LBB0_709:
	s_movk_i32 s3, 0xb00
	v_mad_u64_u32 v[2:3], s[10:11], v108, s3, v[84:85]
	buffer_store_dword v0, v2, s[88:91], 0 offen sc1

.LBB0_713:
	s_movk_i32 s3, 0xb00
	v_mad_u64_u32 v[0:1], s[10:11], v203, s3, v[84:85]
	buffer_store_dword v148, v0, s[88:91], 0 offen sc1
	s_or_b64 exec, exec, s[8:9]
	s_and_b64 vcc, exec, s[6:7]
	s_mov_b64 s[6:7], -1
	s_cbranch_vccnz .LBB0_636

.LBB0_716:
	s_movk_i32 s3, 0xb00
	v_mad_u64_u32 v[80:81], s[10:11], v85, s3, v[84:85]
	buffer_store_dword v193, v80, s[88:91], 0 offen sc1
	s_or_b64 exec, exec, s[8:9]
	s_and_saveexec_b64 s[8:9], s[44:45]
	s_cbranch_execz .LBB0_678
.LBB0_717:
	s_movk_i32 s3, 0xb00
	v_mad_u64_u32 v[80:81], s[10:11], v204, s3, v[84:85]
	buffer_store_dword v192, v80, s[88:91], 0 offen sc1
	s_or_b64 exec, exec, s[8:9]
	s_and_saveexec_b64 s[8:9], s[46:47]
	s_cbranch_execz .LBB0_679
.LBB0_718:
	s_movk_i32 s3, 0xb00
	v_mad_u64_u32 v[80:81], s[10:11], v205, s3, v[84:85]
	buffer_store_dword v169, v80, s[88:91], 0 offen sc1
	s_or_b64 exec, exec, s[8:9]
	s_and_saveexec_b64 s[8:9], s[48:49]
	s_cbranch_execz .LBB0_680
.LBB0_719:
	s_movk_i32 s3, 0xb00
	v_mad_u64_u32 v[80:81], s[10:11], v206, s3, v[84:85]
	buffer_store_dword v168, v80, s[88:91], 0 offen sc1
	s_or_b64 exec, exec, s[8:9]
	s_and_saveexec_b64 s[8:9], s[50:51]
	s_cbranch_execz .LBB0_681
.LBB0_720:
	s_movk_i32 s3, 0xb00
	v_mad_u64_u32 v[80:81], s[10:11], v207, s3, v[84:85]
	buffer_store_dword v165, v80, s[88:91], 0 offen sc1
	s_or_b64 exec, exec, s[8:9]
	s_and_saveexec_b64 s[8:9], s[52:53]
	s_cbranch_execz .LBB0_682
.LBB0_721:
	s_movk_i32 s3, 0xb00
	v_mad_u64_u32 v[80:81], s[10:11], v208, s3, v[84:85]
	buffer_store_dword v164, v80, s[88:91], 0 offen sc1
	s_or_b64 exec, exec, s[8:9]
	s_and_saveexec_b64 s[8:9], s[54:55]
	s_cbranch_execnz .LBB0_683
	s_branch .LBB0_684
.LBB0_722:
	s_movk_i32 s3, 0xb00
	v_mad_u64_u32 v[2:3], s[10:11], v102, s3, v[84:85]
	buffer_store_dword v12, v2, s[88:91], 0 offen sc1
	s_or_b64 exec, exec, s[8:9]
	s_and_saveexec_b64 s[8:9], s[12:13]
	s_cbranch_execz .LBB0_704
.LBB0_723:
	s_movk_i32 s3, 0xb00
	v_mad_u64_u32 v[2:3], s[10:11], v103, s3, v[84:85]
	buffer_store_dword v9, v2, s[88:91], 0 offen sc1
	s_or_b64 exec, exec, s[8:9]
	s_and_saveexec_b64 s[8:9], s[14:15]
	s_cbranch_execz .LBB0_705
.LBB0_724:
	s_movk_i32 s3, 0xb00
	v_mad_u64_u32 v[2:3], s[10:11], v104, s3, v[84:85]
	buffer_store_dword v8, v2, s[88:91], 0 offen sc1
	s_or_b64 exec, exec, s[8:9]
	s_and_saveexec_b64 s[8:9], s[16:17]
	s_cbranch_execz .LBB0_706
.LBB0_725:
	s_movk_i32 s3, 0xb00
	v_mad_u64_u32 v[2:3], s[10:11], v105, s3, v[84:85]
	buffer_store_dword v5, v2, s[88:91], 0 offen sc1
	s_or_b64 exec, exec, s[8:9]
	s_and_saveexec_b64 s[8:9], s[18:19]
	s_cbranch_execz .LBB0_707
.LBB0_726:
	s_movk_i32 s3, 0xb00
	v_mad_u64_u32 v[2:3], s[10:11], v106, s3, v[84:85]
	buffer_store_dword v4, v2, s[88:91], 0 offen sc1
	s_or_b64 exec, exec, s[8:9]
	s_and_saveexec_b64 s[8:9], s[20:21]
	s_cbranch_execz .LBB0_708
.LBB0_727:
	s_movk_i32 s3, 0xb00
	v_mad_u64_u32 v[2:3], s[10:11], v107, s3, v[84:85]
	buffer_store_dword v1, v2, s[88:91], 0 offen sc1
	s_movk_i32 s81, 0x4000
	s_or_b64 exec, exec, s[8:9]
	s_and_saveexec_b64 s[8:9], s[22:23]
	s_cbranch_execnz .LBB0_709
	s_branch .LBB0_710
